# v34 plus 64-byte alignment of the 15 GEMM K-loop head labels (code placement)
# speedup vs baseline: 1.0107x; 1.0014x over previous
; template <class Epi>
; DEVI void gemm_phase(LAS unsigned char* lds, const bf16_t* gA, const bf16_t* gBt, const int lda, const int ldb, const int K, const StaticOrder S_, const Epi E) {
;     ...
;     for (;;) {
;         const bool has_next = S_.next(ui + 1, nxt);
;         const char* nA = has_next ? (const char*)gA + (size_t)nxt.pm * tstepA : cA; const char* nB = has_next ? (const char*)gBt + (size_t)nxt.pn * tstepB : cB;
;         for (int t = 0; t < nt; t += 2) {
;             const bool last = (t == nt - 2);
;             const char* a1 = cA + (size_t)(t + 1) * kstep;
;             const char* a2 = last ? nA : cA + (size_t)(t + 2) * kstep; const char* b2 = last ? nB : cB + (size_t)(t + 2) * kstep;
;     ...
;         for (int a = 0; a < 2; ++a)
; #pragma unroll
;             for (int b = 0; b < 2; ++b)
; #pragma unroll
;                 for (int m = 0; m < 4; ++m)
; #pragma unroll
;                     for (int n = 0; n < 2; ++n) acc[a][b][m][n] = (f32x4){0.f, 0.f, 0.f, 0.f};
.LBB0_257:
	v_mov_b32_e32 v123, 0
	s_andn2_b64 vcc, exec, s[18:19]
	v_mov_b32_e32 v122, v123
	v_mov_b32_e32 v121, v123
	v_mov_b32_e32 v120, v123
	v_mov_b32_e32 v119, v123
	v_mov_b32_e32 v118, v123
	v_mov_b32_e32 v117, v123
	v_mov_b32_e32 v116, v123
	v_mov_b32_e32 v111, v123
	v_mov_b32_e32 v110, v123
	v_mov_b32_e32 v109, v123
	v_mov_b32_e32 v108, v123
	v_mov_b32_e32 v103, v123
	v_mov_b32_e32 v102, v123
	v_mov_b32_e32 v101, v123
	v_mov_b32_e32 v100, v123
	v_mov_b32_e32 v95, v123
	v_mov_b32_e32 v94, v123
	v_mov_b32_e32 v93, v123
	v_mov_b32_e32 v92, v123
	v_mov_b32_e32 v87, v123
	v_mov_b32_e32 v86, v123
	v_mov_b32_e32 v85, v123
	v_mov_b32_e32 v84, v123
	v_mov_b32_e32 v79, v123
	v_mov_b32_e32 v78, v123
	v_mov_b32_e32 v77, v123
	v_mov_b32_e32 v76, v123
	v_mov_b32_e32 v71, v123
	v_mov_b32_e32 v70, v123
	v_mov_b32_e32 v69, v123
	v_mov_b32_e32 v68, v123
	v_mov_b32_e32 v127, v123
	v_mov_b32_e32 v126, v123
	v_mov_b32_e32 v125, v123
	v_mov_b32_e32 v124, v123
	v_mov_b32_e32 v115, v123
	v_mov_b32_e32 v114, v123
	v_mov_b32_e32 v113, v123
	v_mov_b32_e32 v112, v123
	v_mov_b32_e32 v107, v123
	v_mov_b32_e32 v106, v123
	v_mov_b32_e32 v105, v123
	v_mov_b32_e32 v104, v123
	v_mov_b32_e32 v99, v123
	v_mov_b32_e32 v98, v123
	v_mov_b32_e32 v97, v123
	v_mov_b32_e32 v96, v123
	v_mov_b32_e32 v91, v123
	v_mov_b32_e32 v90, v123
	v_mov_b32_e32 v89, v123
	v_mov_b32_e32 v88, v123
	v_mov_b32_e32 v83, v123
	v_mov_b32_e32 v82, v123
	v_mov_b32_e32 v81, v123
	v_mov_b32_e32 v80, v123
	v_mov_b32_e32 v75, v123
	v_mov_b32_e32 v74, v123
	v_mov_b32_e32 v73, v123
	v_mov_b32_e32 v72, v123
	v_mov_b32_e32 v67, v123
	v_mov_b32_e32 v66, v123
	v_mov_b32_e32 v65, v123
	v_mov_b32_e32 v64, v123
	v_mov_b32_e32 v63, v123
	v_mov_b32_e32 v62, v123
	v_mov_b32_e32 v61, v123
	v_mov_b32_e32 v60, v123
	v_mov_b32_e32 v59, v123
	v_mov_b32_e32 v58, v123
	v_mov_b32_e32 v57, v123
	v_mov_b32_e32 v56, v123
	v_mov_b32_e32 v47, v123
	v_mov_b32_e32 v46, v123
	v_mov_b32_e32 v45, v123
	v_mov_b32_e32 v44, v123
	v_mov_b32_e32 v43, v123
	v_mov_b32_e32 v42, v123
	v_mov_b32_e32 v41, v123
	v_mov_b32_e32 v40, v123
	v_mov_b32_e32 v31, v123
	v_mov_b32_e32 v30, v123
	v_mov_b32_e32 v29, v123
	v_mov_b32_e32 v28, v123
	v_mov_b32_e32 v27, v123
	v_mov_b32_e32 v26, v123
	v_mov_b32_e32 v25, v123
	v_mov_b32_e32 v24, v123
	v_mov_b32_e32 v15, v123
	v_mov_b32_e32 v14, v123
	v_mov_b32_e32 v13, v123
	v_mov_b32_e32 v12, v123
	v_mov_b32_e32 v11, v123
	v_mov_b32_e32 v10, v123
	v_mov_b32_e32 v9, v123
	v_mov_b32_e32 v8, v123
	v_mov_b32_e32 v55, v123
	v_mov_b32_e32 v54, v123
	v_mov_b32_e32 v53, v123
	v_mov_b32_e32 v52, v123
	v_mov_b32_e32 v51, v123
	v_mov_b32_e32 v50, v123
	v_mov_b32_e32 v49, v123
	v_mov_b32_e32 v48, v123
	v_mov_b32_e32 v39, v123
	v_mov_b32_e32 v38, v123
	v_mov_b32_e32 v37, v123
	v_mov_b32_e32 v36, v123
	v_mov_b32_e32 v35, v123
	v_mov_b32_e32 v34, v123
	v_mov_b32_e32 v33, v123
	v_mov_b32_e32 v32, v123
	v_mov_b32_e32 v23, v123
	v_mov_b32_e32 v22, v123
	v_mov_b32_e32 v21, v123
	v_mov_b32_e32 v20, v123
	v_mov_b32_e32 v19, v123
	v_mov_b32_e32 v18, v123
	v_mov_b32_e32 v17, v123
	v_mov_b32_e32 v16, v123
	v_mov_b32_e32 v7, v123
	v_mov_b32_e32 v6, v123
	v_mov_b32_e32 v5, v123
	v_mov_b32_e32 v4, v123
	v_mov_b32_e32 v3, v123
	v_mov_b32_e32 v2, v123
	v_mov_b32_e32 v1, v123
	v_mov_b32_e32 v0, v123
	s_cbranch_vccnz .LBB0_260
	s_add_u32 s24, s24, 0x80
	s_addc_u32 s25, s25, 0
	s_add_u32 s77, s26, 0x100
	v_mov_b32_e32 v0, 0
	s_addc_u32 s78, s27, 0
	s_mov_b32 s26, 0
	v_mov_b32_e32 v1, v0
	v_mov_b32_e32 v2, v0
	v_mov_b32_e32 v3, v0
	v_mov_b32_e32 v4, v0
	v_mov_b32_e32 v5, v0
	v_mov_b32_e32 v6, v0
	v_mov_b32_e32 v7, v0
	v_mov_b32_e32 v16, v0
	v_mov_b32_e32 v17, v0
	v_mov_b32_e32 v18, v0
	v_mov_b32_e32 v19, v0
	v_mov_b32_e32 v20, v0
	v_mov_b32_e32 v21, v0
	v_mov_b32_e32 v22, v0
	v_mov_b32_e32 v23, v0
	v_mov_b32_e32 v32, v0
	v_mov_b32_e32 v33, v0
	v_mov_b32_e32 v34, v0
	v_mov_b32_e32 v35, v0
	v_mov_b32_e32 v36, v0
	v_mov_b32_e32 v37, v0
	v_mov_b32_e32 v38, v0
	v_mov_b32_e32 v39, v0
	v_mov_b32_e32 v48, v0
	v_mov_b32_e32 v49, v0
	v_mov_b32_e32 v50, v0
	v_mov_b32_e32 v51, v0
	v_mov_b32_e32 v52, v0
	v_mov_b32_e32 v53, v0
	v_mov_b32_e32 v54, v0
	v_mov_b32_e32 v55, v0
	v_mov_b32_e32 v8, v0
	v_mov_b32_e32 v9, v0
	v_mov_b32_e32 v10, v0
	v_mov_b32_e32 v11, v0
	v_mov_b32_e32 v12, v0
	v_mov_b32_e32 v13, v0
	v_mov_b32_e32 v14, v0
	v_mov_b32_e32 v15, v0
	v_mov_b32_e32 v24, v0
	v_mov_b32_e32 v25, v0
	v_mov_b32_e32 v26, v0
	v_mov_b32_e32 v27, v0
	v_mov_b32_e32 v28, v0
	v_mov_b32_e32 v29, v0
	v_mov_b32_e32 v30, v0
	v_mov_b32_e32 v31, v0
	v_mov_b32_e32 v40, v0
	v_mov_b32_e32 v41, v0
	v_mov_b32_e32 v42, v0
	v_mov_b32_e32 v43, v0
	v_mov_b32_e32 v44, v0
	v_mov_b32_e32 v45, v0
	v_mov_b32_e32 v46, v0
	v_mov_b32_e32 v47, v0
	v_mov_b32_e32 v56, v0
	v_mov_b32_e32 v57, v0
	v_mov_b32_e32 v58, v0
	v_mov_b32_e32 v59, v0
	v_mov_b32_e32 v60, v0
	v_mov_b32_e32 v61, v0
	v_mov_b32_e32 v62, v0
	v_mov_b32_e32 v63, v0
	v_mov_b32_e32 v64, v0
	v_mov_b32_e32 v65, v0
	v_mov_b32_e32 v66, v0
	v_mov_b32_e32 v67, v0
	v_mov_b32_e32 v72, v0
	v_mov_b32_e32 v73, v0
	v_mov_b32_e32 v74, v0
	v_mov_b32_e32 v75, v0
	v_mov_b32_e32 v80, v0
	v_mov_b32_e32 v81, v0
	v_mov_b32_e32 v82, v0
	v_mov_b32_e32 v83, v0
	v_mov_b32_e32 v88, v0
	v_mov_b32_e32 v89, v0
	v_mov_b32_e32 v90, v0
	v_mov_b32_e32 v91, v0
	v_mov_b32_e32 v96, v0
	v_mov_b32_e32 v97, v0
	v_mov_b32_e32 v98, v0
	v_mov_b32_e32 v99, v0
	v_mov_b32_e32 v104, v0
	v_mov_b32_e32 v105, v0
	v_mov_b32_e32 v106, v0
	v_mov_b32_e32 v107, v0
	v_mov_b32_e32 v112, v0
	v_mov_b32_e32 v113, v0
	v_mov_b32_e32 v114, v0
	v_mov_b32_e32 v115, v0
	v_mov_b32_e32 v124, v0
	v_mov_b32_e32 v125, v0
	v_mov_b32_e32 v126, v0
	v_mov_b32_e32 v127, v0
	v_mov_b32_e32 v68, v0
	v_mov_b32_e32 v69, v0
	v_mov_b32_e32 v70, v0
	v_mov_b32_e32 v71, v0
	v_mov_b32_e32 v76, v0
	v_mov_b32_e32 v77, v0
	v_mov_b32_e32 v78, v0
	v_mov_b32_e32 v79, v0
	v_mov_b32_e32 v84, v0
	v_mov_b32_e32 v85, v0
	v_mov_b32_e32 v86, v0
	v_mov_b32_e32 v87, v0
	v_mov_b32_e32 v92, v0
	v_mov_b32_e32 v93, v0
	v_mov_b32_e32 v94, v0
	v_mov_b32_e32 v95, v0
	v_mov_b32_e32 v100, v0
	v_mov_b32_e32 v101, v0
	v_mov_b32_e32 v102, v0
	v_mov_b32_e32 v103, v0
	v_mov_b32_e32 v108, v0
	v_mov_b32_e32 v109, v0
	v_mov_b32_e32 v110, v0
	v_mov_b32_e32 v111, v0
	v_mov_b32_e32 v116, v0
	v_mov_b32_e32 v117, v0
	v_mov_b32_e32 v118, v0
	v_mov_b32_e32 v119, v0
	v_mov_b32_e32 v120, v0
	v_mov_b32_e32 v121, v0
	v_mov_b32_e32 v122, v0
	v_mov_b32_e32 v123, v0
	.p2alignl 6, 3212836864

; template <class Epi>
; DEVI void gemm_phase(LAS unsigned char* lds, const bf16_t* gA, const bf16_t* gBt, const int lda, const int ldb, const int K, const StaticOrder S_, const Epi E) {
;     ...
;     for (;;) {
;         const bool has_next = S_.next(ui + 1, nxt);
;         const char* nA = has_next ? (const char*)gA + (size_t)nxt.pm * tstepA : cA; const char* nB = has_next ? (const char*)gBt + (size_t)nxt.pn * tstepB : cB;
;         for (int t = 0; t < nt; t += 2) {
;             const bool last = (t == nt - 2);
;             const char* a1 = cA + (size_t)(t + 1) * kstep;
;             const char* a2 = last ? nA : cA + (size_t)(t + 2) * kstep; const char* b2 = last ? nB : cB + (size_t)(t + 2) * kstep;
;     ...
;         for (int a = 0; a < 2; ++a)
; #pragma unroll
;             for (int b = 0; b < 2; ++b)
; #pragma unroll
;                 for (int m = 0; m < 4; ++m)
; #pragma unroll
;                     for (int n = 0; n < 2; ++n) acc[a][b][m][n] = (f32x4){0.f, 0.f, 0.f, 0.f};
.LBB0_386:
	v_mov_b32_e32 v127, 0
	s_andn2_b64 vcc, exec, s[44:45]
	v_mov_b32_e32 v126, v127
	v_mov_b32_e32 v125, v127
	v_mov_b32_e32 v124, v127
	v_mov_b32_e32 v123, v127
	v_mov_b32_e32 v122, v127
	v_mov_b32_e32 v121, v127
	v_mov_b32_e32 v120, v127
	v_mov_b32_e32 v111, v127
	v_mov_b32_e32 v110, v127
	v_mov_b32_e32 v109, v127
	v_mov_b32_e32 v108, v127
	v_mov_b32_e32 v107, v127
	v_mov_b32_e32 v106, v127
	v_mov_b32_e32 v105, v127
	v_mov_b32_e32 v104, v127
	v_mov_b32_e32 v95, v127
	v_mov_b32_e32 v94, v127
	v_mov_b32_e32 v93, v127
	v_mov_b32_e32 v92, v127
	v_mov_b32_e32 v91, v127
	v_mov_b32_e32 v90, v127
	v_mov_b32_e32 v89, v127
	v_mov_b32_e32 v88, v127
	v_mov_b32_e32 v79, v127
	v_mov_b32_e32 v78, v127
	v_mov_b32_e32 v77, v127
	v_mov_b32_e32 v76, v127
	v_mov_b32_e32 v75, v127
	v_mov_b32_e32 v74, v127
	v_mov_b32_e32 v73, v127
	v_mov_b32_e32 v72, v127
	v_mov_b32_e32 v119, v127
	v_mov_b32_e32 v118, v127
	v_mov_b32_e32 v117, v127
	v_mov_b32_e32 v116, v127
	v_mov_b32_e32 v115, v127
	v_mov_b32_e32 v114, v127
	v_mov_b32_e32 v113, v127
	v_mov_b32_e32 v112, v127
	v_mov_b32_e32 v103, v127
	v_mov_b32_e32 v102, v127
	v_mov_b32_e32 v101, v127
	v_mov_b32_e32 v100, v127
	v_mov_b32_e32 v99, v127
	v_mov_b32_e32 v98, v127
	v_mov_b32_e32 v97, v127
	v_mov_b32_e32 v96, v127
	v_mov_b32_e32 v87, v127
	v_mov_b32_e32 v86, v127
	v_mov_b32_e32 v85, v127
	v_mov_b32_e32 v84, v127
	v_mov_b32_e32 v83, v127
	v_mov_b32_e32 v82, v127
	v_mov_b32_e32 v81, v127
	v_mov_b32_e32 v80, v127
	v_mov_b32_e32 v71, v127
	v_mov_b32_e32 v70, v127
	v_mov_b32_e32 v69, v127
	v_mov_b32_e32 v68, v127
	v_mov_b32_e32 v67, v127
	v_mov_b32_e32 v66, v127
	v_mov_b32_e32 v65, v127
	v_mov_b32_e32 v64, v127
	v_mov_b32_e32 v63, v127
	v_mov_b32_e32 v62, v127
	v_mov_b32_e32 v61, v127
	v_mov_b32_e32 v60, v127
	v_mov_b32_e32 v59, v127
	v_mov_b32_e32 v58, v127
	v_mov_b32_e32 v57, v127
	v_mov_b32_e32 v56, v127
	v_mov_b32_e32 v47, v127
	v_mov_b32_e32 v46, v127
	v_mov_b32_e32 v45, v127
	v_mov_b32_e32 v44, v127
	v_mov_b32_e32 v43, v127
	v_mov_b32_e32 v42, v127
	v_mov_b32_e32 v41, v127
	v_mov_b32_e32 v40, v127
	v_mov_b32_e32 v31, v127
	v_mov_b32_e32 v30, v127
	v_mov_b32_e32 v29, v127
	v_mov_b32_e32 v28, v127
	v_mov_b32_e32 v27, v127
	v_mov_b32_e32 v26, v127
	v_mov_b32_e32 v25, v127
	v_mov_b32_e32 v24, v127
	v_mov_b32_e32 v15, v127
	v_mov_b32_e32 v14, v127
	v_mov_b32_e32 v13, v127
	v_mov_b32_e32 v12, v127
	v_mov_b32_e32 v11, v127
	v_mov_b32_e32 v10, v127
	v_mov_b32_e32 v9, v127
	v_mov_b32_e32 v8, v127
	v_mov_b32_e32 v55, v127
	v_mov_b32_e32 v54, v127
	v_mov_b32_e32 v53, v127
	v_mov_b32_e32 v52, v127
	v_mov_b32_e32 v51, v127
	v_mov_b32_e32 v50, v127
	v_mov_b32_e32 v49, v127
	v_mov_b32_e32 v48, v127
	v_mov_b32_e32 v39, v127
	v_mov_b32_e32 v38, v127
	v_mov_b32_e32 v37, v127
	v_mov_b32_e32 v36, v127
	v_mov_b32_e32 v35, v127
	v_mov_b32_e32 v34, v127
	v_mov_b32_e32 v33, v127
	v_mov_b32_e32 v32, v127
	v_mov_b32_e32 v23, v127
	v_mov_b32_e32 v22, v127
	v_mov_b32_e32 v21, v127
	v_mov_b32_e32 v20, v127
	v_mov_b32_e32 v19, v127
	v_mov_b32_e32 v18, v127
	v_mov_b32_e32 v17, v127
	v_mov_b32_e32 v16, v127
	v_mov_b32_e32 v7, v127
	v_mov_b32_e32 v6, v127
	v_mov_b32_e32 v5, v127
	v_mov_b32_e32 v4, v127
	v_mov_b32_e32 v3, v127
	v_mov_b32_e32 v2, v127
	s_waitcnt lgkmcnt(0)
	v_mov_b32_e32 v1, v127
	v_mov_b32_e32 v0, v127
	s_cbranch_vccnz .LBB0_389
	s_add_u32 s14, s14, 0x80
	s_addc_u32 s15, s15, 0
	s_add_u32 s72, s16, 0x100
	v_mov_b32_e32 v0, 0
	s_addc_u32 s73, s17, 0
	s_mov_b32 s16, 0
	v_mov_b32_e32 v1, v0
	v_mov_b32_e32 v2, v0
	v_mov_b32_e32 v3, v0
	v_mov_b32_e32 v4, v0
	v_mov_b32_e32 v5, v0
	v_mov_b32_e32 v6, v0
	v_mov_b32_e32 v7, v0
	v_mov_b32_e32 v16, v0
	v_mov_b32_e32 v17, v0
	v_mov_b32_e32 v18, v0
	v_mov_b32_e32 v19, v0
	v_mov_b32_e32 v20, v0
	v_mov_b32_e32 v21, v0
	v_mov_b32_e32 v22, v0
	v_mov_b32_e32 v23, v0
	v_mov_b32_e32 v32, v0
	v_mov_b32_e32 v33, v0
	v_mov_b32_e32 v34, v0
	v_mov_b32_e32 v35, v0
	v_mov_b32_e32 v36, v0
	v_mov_b32_e32 v37, v0
	v_mov_b32_e32 v38, v0
	v_mov_b32_e32 v39, v0
	v_mov_b32_e32 v48, v0
	v_mov_b32_e32 v49, v0
	v_mov_b32_e32 v50, v0
	v_mov_b32_e32 v51, v0
	v_mov_b32_e32 v52, v0
	v_mov_b32_e32 v53, v0
	v_mov_b32_e32 v54, v0
	v_mov_b32_e32 v55, v0
	v_mov_b32_e32 v8, v0
	v_mov_b32_e32 v9, v0
	v_mov_b32_e32 v10, v0
	v_mov_b32_e32 v11, v0
	v_mov_b32_e32 v12, v0
	v_mov_b32_e32 v13, v0
	v_mov_b32_e32 v14, v0
	v_mov_b32_e32 v15, v0
	v_mov_b32_e32 v24, v0
	v_mov_b32_e32 v25, v0
	v_mov_b32_e32 v26, v0
	v_mov_b32_e32 v27, v0
	v_mov_b32_e32 v28, v0
	v_mov_b32_e32 v29, v0
	v_mov_b32_e32 v30, v0
	v_mov_b32_e32 v31, v0
	v_mov_b32_e32 v40, v0
	v_mov_b32_e32 v41, v0
	v_mov_b32_e32 v42, v0
	v_mov_b32_e32 v43, v0
	v_mov_b32_e32 v44, v0
	v_mov_b32_e32 v45, v0
	v_mov_b32_e32 v46, v0
	v_mov_b32_e32 v47, v0
	v_mov_b32_e32 v56, v0
	v_mov_b32_e32 v57, v0
	v_mov_b32_e32 v58, v0
	v_mov_b32_e32 v59, v0
	v_mov_b32_e32 v60, v0
	v_mov_b32_e32 v61, v0
	v_mov_b32_e32 v62, v0
	v_mov_b32_e32 v63, v0
	v_mov_b32_e32 v64, v0
	v_mov_b32_e32 v65, v0
	v_mov_b32_e32 v66, v0
	v_mov_b32_e32 v67, v0
	v_mov_b32_e32 v68, v0
	v_mov_b32_e32 v69, v0
	v_mov_b32_e32 v70, v0
	v_mov_b32_e32 v71, v0
	v_mov_b32_e32 v80, v0
	v_mov_b32_e32 v81, v0
	v_mov_b32_e32 v82, v0
	v_mov_b32_e32 v83, v0
	v_mov_b32_e32 v84, v0
	v_mov_b32_e32 v85, v0
	v_mov_b32_e32 v86, v0
	v_mov_b32_e32 v87, v0
	v_mov_b32_e32 v96, v0
	v_mov_b32_e32 v97, v0
	v_mov_b32_e32 v98, v0
	v_mov_b32_e32 v99, v0
	v_mov_b32_e32 v100, v0
	v_mov_b32_e32 v101, v0
	v_mov_b32_e32 v102, v0
	v_mov_b32_e32 v103, v0
	v_mov_b32_e32 v112, v0
	v_mov_b32_e32 v113, v0
	v_mov_b32_e32 v114, v0
	v_mov_b32_e32 v115, v0
	v_mov_b32_e32 v116, v0
	v_mov_b32_e32 v117, v0
	v_mov_b32_e32 v118, v0
	v_mov_b32_e32 v119, v0
	v_mov_b32_e32 v72, v0
	v_mov_b32_e32 v73, v0
	v_mov_b32_e32 v74, v0
	v_mov_b32_e32 v75, v0
	v_mov_b32_e32 v76, v0
	v_mov_b32_e32 v77, v0
	v_mov_b32_e32 v78, v0
	v_mov_b32_e32 v79, v0
	v_mov_b32_e32 v88, v0
	v_mov_b32_e32 v89, v0
	v_mov_b32_e32 v90, v0
	v_mov_b32_e32 v91, v0
	v_mov_b32_e32 v92, v0
	v_mov_b32_e32 v93, v0
	v_mov_b32_e32 v94, v0
	v_mov_b32_e32 v95, v0
	v_mov_b32_e32 v104, v0
	v_mov_b32_e32 v105, v0
	v_mov_b32_e32 v106, v0
	v_mov_b32_e32 v107, v0
	v_mov_b32_e32 v108, v0
	v_mov_b32_e32 v109, v0
	v_mov_b32_e32 v110, v0
	v_mov_b32_e32 v111, v0
	v_mov_b32_e32 v120, v0
	v_mov_b32_e32 v121, v0
	v_mov_b32_e32 v122, v0
	v_mov_b32_e32 v123, v0
	v_mov_b32_e32 v124, v0
	v_mov_b32_e32 v125, v0
	v_mov_b32_e32 v126, v0
	v_mov_b32_e32 v127, v0
	.p2alignl 6, 3212836864

; template <class Epi>
; DEVI void gemm_phase(LAS unsigned char* lds, const bf16_t* gA, const bf16_t* gBt, const int lda, const int ldb, const int K, const StaticOrder S_, const Epi E) {
;     ...
;     for (;;) {
;         const bool has_next = S_.next(ui + 1, nxt);
;         const char* nA = has_next ? (const char*)gA + (size_t)nxt.pm * tstepA : cA; const char* nB = has_next ? (const char*)gBt + (size_t)nxt.pn * tstepB : cB;
;         for (int t = 0; t < nt; t += 2) {
;             const bool last = (t == nt - 2);
;             const char* a1 = cA + (size_t)(t + 1) * kstep;
;             const char* a2 = last ? nA : cA + (size_t)(t + 2) * kstep; const char* b2 = last ? nB : cB + (size_t)(t + 2) * kstep;
;     ...
;         for (int a = 0; a < 2; ++a)
; #pragma unroll
;             for (int b = 0; b < 2; ++b)
; #pragma unroll
;                 for (int m = 0; m < 4; ++m)
; #pragma unroll
;                     for (int n = 0; n < 2; ++n) acc[a][b][m][n] = (f32x4){0.f, 0.f, 0.f, 0.f};
.LBB0_517:
	v_mov_b32_e32 v127, 0
	s_andn2_b64 vcc, exec, s[44:45]
	v_mov_b32_e32 v126, v127
	v_mov_b32_e32 v125, v127
	v_mov_b32_e32 v124, v127
	v_mov_b32_e32 v123, v127
	v_mov_b32_e32 v122, v127
	v_mov_b32_e32 v121, v127
	v_mov_b32_e32 v120, v127
	v_mov_b32_e32 v111, v127
	v_mov_b32_e32 v110, v127
	v_mov_b32_e32 v109, v127
	v_mov_b32_e32 v108, v127
	v_mov_b32_e32 v107, v127
	v_mov_b32_e32 v106, v127
	v_mov_b32_e32 v105, v127
	v_mov_b32_e32 v104, v127
	v_mov_b32_e32 v95, v127
	v_mov_b32_e32 v94, v127
	v_mov_b32_e32 v93, v127
	v_mov_b32_e32 v92, v127
	v_mov_b32_e32 v91, v127
	v_mov_b32_e32 v90, v127
	v_mov_b32_e32 v89, v127
	v_mov_b32_e32 v88, v127
	v_mov_b32_e32 v79, v127
	v_mov_b32_e32 v78, v127
	v_mov_b32_e32 v77, v127
	v_mov_b32_e32 v76, v127
	v_mov_b32_e32 v75, v127
	v_mov_b32_e32 v74, v127
	v_mov_b32_e32 v73, v127
	v_mov_b32_e32 v72, v127
	v_mov_b32_e32 v119, v127
	v_mov_b32_e32 v118, v127
	v_mov_b32_e32 v117, v127
	v_mov_b32_e32 v116, v127
	v_mov_b32_e32 v115, v127
	v_mov_b32_e32 v114, v127
	v_mov_b32_e32 v113, v127
	v_mov_b32_e32 v112, v127
	v_mov_b32_e32 v103, v127
	v_mov_b32_e32 v102, v127
	v_mov_b32_e32 v101, v127
	v_mov_b32_e32 v100, v127
	v_mov_b32_e32 v99, v127
	v_mov_b32_e32 v98, v127
	v_mov_b32_e32 v97, v127
	v_mov_b32_e32 v96, v127
	v_mov_b32_e32 v87, v127
	v_mov_b32_e32 v86, v127
	v_mov_b32_e32 v85, v127
	v_mov_b32_e32 v84, v127
	v_mov_b32_e32 v83, v127
	v_mov_b32_e32 v82, v127
	v_mov_b32_e32 v81, v127
	v_mov_b32_e32 v80, v127
	v_mov_b32_e32 v71, v127
	v_mov_b32_e32 v70, v127
	v_mov_b32_e32 v69, v127
	v_mov_b32_e32 v68, v127
	v_mov_b32_e32 v67, v127
	v_mov_b32_e32 v66, v127
	v_mov_b32_e32 v65, v127
	v_mov_b32_e32 v64, v127
	v_mov_b32_e32 v63, v127
	v_mov_b32_e32 v62, v127
	v_mov_b32_e32 v61, v127
	v_mov_b32_e32 v60, v127
	v_mov_b32_e32 v59, v127
	v_mov_b32_e32 v58, v127
	v_mov_b32_e32 v57, v127
	v_mov_b32_e32 v56, v127
	v_mov_b32_e32 v47, v127
	v_mov_b32_e32 v46, v127
	v_mov_b32_e32 v45, v127
	v_mov_b32_e32 v44, v127
	v_mov_b32_e32 v43, v127
	v_mov_b32_e32 v42, v127
	v_mov_b32_e32 v41, v127
	v_mov_b32_e32 v40, v127
	v_mov_b32_e32 v31, v127
	v_mov_b32_e32 v30, v127
	v_mov_b32_e32 v29, v127
	v_mov_b32_e32 v28, v127
	v_mov_b32_e32 v27, v127
	v_mov_b32_e32 v26, v127
	v_mov_b32_e32 v25, v127
	v_mov_b32_e32 v24, v127
	v_mov_b32_e32 v15, v127
	v_mov_b32_e32 v14, v127
	v_mov_b32_e32 v13, v127
	v_mov_b32_e32 v12, v127
	v_mov_b32_e32 v11, v127
	v_mov_b32_e32 v10, v127
	v_mov_b32_e32 v9, v127
	v_mov_b32_e32 v8, v127
	v_mov_b32_e32 v55, v127
	v_mov_b32_e32 v54, v127
	v_mov_b32_e32 v53, v127
	v_mov_b32_e32 v52, v127
	v_mov_b32_e32 v51, v127
	v_mov_b32_e32 v50, v127
	v_mov_b32_e32 v49, v127
	v_mov_b32_e32 v48, v127
	v_mov_b32_e32 v39, v127
	v_mov_b32_e32 v38, v127
	v_mov_b32_e32 v37, v127
	v_mov_b32_e32 v36, v127
	v_mov_b32_e32 v35, v127
	v_mov_b32_e32 v34, v127
	v_mov_b32_e32 v33, v127
	v_mov_b32_e32 v32, v127
	v_mov_b32_e32 v23, v127
	v_mov_b32_e32 v22, v127
	v_mov_b32_e32 v21, v127
	v_mov_b32_e32 v20, v127
	v_mov_b32_e32 v19, v127
	v_mov_b32_e32 v18, v127
	v_mov_b32_e32 v17, v127
	v_mov_b32_e32 v16, v127
	v_mov_b32_e32 v7, v127
	v_mov_b32_e32 v6, v127
	v_mov_b32_e32 v5, v127
	v_mov_b32_e32 v4, v127
	v_mov_b32_e32 v3, v127
	v_mov_b32_e32 v2, v127
	v_mov_b32_e32 v1, v127
	v_mov_b32_e32 v0, v127
	s_cbranch_vccnz .LBB0_521
	s_add_u32 s14, s14, 0x80
	s_addc_u32 s15, s15, 0
	s_add_u32 s68, s68, 0x100
	v_mov_b32_e32 v0, 0
	s_addc_u32 s69, s69, 0
	s_mov_b32 s16, 0
	v_mov_b32_e32 v1, v0
	v_mov_b32_e32 v2, v0
	v_mov_b32_e32 v3, v0
	v_mov_b32_e32 v4, v0
	v_mov_b32_e32 v5, v0
	v_mov_b32_e32 v6, v0
	v_mov_b32_e32 v7, v0
	v_mov_b32_e32 v16, v0
	v_mov_b32_e32 v17, v0
	v_mov_b32_e32 v18, v0
	v_mov_b32_e32 v19, v0
	v_mov_b32_e32 v20, v0
	v_mov_b32_e32 v21, v0
	v_mov_b32_e32 v22, v0
	v_mov_b32_e32 v23, v0
	v_mov_b32_e32 v32, v0
	v_mov_b32_e32 v33, v0
	v_mov_b32_e32 v34, v0
	v_mov_b32_e32 v35, v0
	v_mov_b32_e32 v36, v0
	v_mov_b32_e32 v37, v0
	v_mov_b32_e32 v38, v0
	v_mov_b32_e32 v39, v0
	v_mov_b32_e32 v48, v0
	v_mov_b32_e32 v49, v0
	v_mov_b32_e32 v50, v0
	v_mov_b32_e32 v51, v0
	v_mov_b32_e32 v52, v0
	v_mov_b32_e32 v53, v0
	v_mov_b32_e32 v54, v0
	v_mov_b32_e32 v55, v0
	v_mov_b32_e32 v8, v0
	v_mov_b32_e32 v9, v0
	v_mov_b32_e32 v10, v0
	v_mov_b32_e32 v11, v0
	v_mov_b32_e32 v12, v0
	v_mov_b32_e32 v13, v0
	v_mov_b32_e32 v14, v0
	v_mov_b32_e32 v15, v0
	v_mov_b32_e32 v24, v0
	v_mov_b32_e32 v25, v0
	v_mov_b32_e32 v26, v0
	v_mov_b32_e32 v27, v0
	v_mov_b32_e32 v28, v0
	v_mov_b32_e32 v29, v0
	v_mov_b32_e32 v30, v0
	v_mov_b32_e32 v31, v0
	v_mov_b32_e32 v40, v0
	v_mov_b32_e32 v41, v0
	v_mov_b32_e32 v42, v0
	v_mov_b32_e32 v43, v0
	v_mov_b32_e32 v44, v0
	v_mov_b32_e32 v45, v0
	v_mov_b32_e32 v46, v0
	v_mov_b32_e32 v47, v0
	v_mov_b32_e32 v56, v0
	v_mov_b32_e32 v57, v0
	v_mov_b32_e32 v58, v0
	v_mov_b32_e32 v59, v0
	v_mov_b32_e32 v60, v0
	v_mov_b32_e32 v61, v0
	v_mov_b32_e32 v62, v0
	v_mov_b32_e32 v63, v0
	v_mov_b32_e32 v64, v0
	v_mov_b32_e32 v65, v0
	v_mov_b32_e32 v66, v0
	v_mov_b32_e32 v67, v0
	v_mov_b32_e32 v68, v0
	v_mov_b32_e32 v69, v0
	v_mov_b32_e32 v70, v0
	v_mov_b32_e32 v71, v0
	v_mov_b32_e32 v80, v0
	v_mov_b32_e32 v81, v0
	v_mov_b32_e32 v82, v0
	v_mov_b32_e32 v83, v0
	v_mov_b32_e32 v84, v0
	v_mov_b32_e32 v85, v0
	v_mov_b32_e32 v86, v0
	v_mov_b32_e32 v87, v0
	v_mov_b32_e32 v96, v0
	v_mov_b32_e32 v97, v0
	v_mov_b32_e32 v98, v0
	v_mov_b32_e32 v99, v0
	v_mov_b32_e32 v100, v0
	v_mov_b32_e32 v101, v0
	v_mov_b32_e32 v102, v0
	v_mov_b32_e32 v103, v0
	v_mov_b32_e32 v112, v0
	v_mov_b32_e32 v113, v0
	v_mov_b32_e32 v114, v0
	v_mov_b32_e32 v115, v0
	v_mov_b32_e32 v116, v0
	v_mov_b32_e32 v117, v0
	v_mov_b32_e32 v118, v0
	v_mov_b32_e32 v119, v0
	v_mov_b32_e32 v72, v0
	v_mov_b32_e32 v73, v0
	v_mov_b32_e32 v74, v0
	v_mov_b32_e32 v75, v0
	v_mov_b32_e32 v76, v0
	v_mov_b32_e32 v77, v0
	v_mov_b32_e32 v78, v0
	v_mov_b32_e32 v79, v0
	v_mov_b32_e32 v88, v0
	v_mov_b32_e32 v89, v0
	v_mov_b32_e32 v90, v0
	v_mov_b32_e32 v91, v0
	v_mov_b32_e32 v92, v0
	v_mov_b32_e32 v93, v0
	v_mov_b32_e32 v94, v0
	v_mov_b32_e32 v95, v0
	v_mov_b32_e32 v104, v0
	v_mov_b32_e32 v105, v0
	v_mov_b32_e32 v106, v0
	v_mov_b32_e32 v107, v0
	v_mov_b32_e32 v108, v0
	v_mov_b32_e32 v109, v0
	v_mov_b32_e32 v110, v0
	v_mov_b32_e32 v111, v0
	v_mov_b32_e32 v120, v0
	v_mov_b32_e32 v121, v0
	v_mov_b32_e32 v122, v0
	v_mov_b32_e32 v123, v0
	v_mov_b32_e32 v124, v0
	v_mov_b32_e32 v125, v0
	v_mov_b32_e32 v126, v0
	v_mov_b32_e32 v127, v0
	.p2alignl 6, 3212836864

; template <class Epi>
; DEVI void gemm_phase(LAS unsigned char* lds, const bf16_t* gA, const bf16_t* gBt, const int lda, const int ldb, const int K, const StaticOrder S_, const Epi E) {
;     ...
;     for (;;) {
;         const bool has_next = S_.next(ui + 1, nxt);
;         const char* nA = has_next ? (const char*)gA + (size_t)nxt.pm * tstepA : cA; const char* nB = has_next ? (const char*)gBt + (size_t)nxt.pn * tstepB : cB;
;         for (int t = 0; t < nt; t += 2) {
;             const bool last = (t == nt - 2);
;             const char* a1 = cA + (size_t)(t + 1) * kstep;
;             const char* a2 = last ? nA : cA + (size_t)(t + 2) * kstep; const char* b2 = last ? nB : cB + (size_t)(t + 2) * kstep;
;     ...
;         for (int a = 0; a < 2; ++a)
; #pragma unroll
;             for (int b = 0; b < 2; ++b)
; #pragma unroll
;                 for (int m = 0; m < 4; ++m)
; #pragma unroll
;                     for (int n = 0; n < 2; ++n) acc[a][b][m][n] = (f32x4){0.f, 0.f, 0.f, 0.f};
.LBB0_742:
	v_mov_b32_e32 v127, 0
	s_andn2_b64 vcc, exec, s[44:45]
	v_mov_b32_e32 v126, v127
	v_mov_b32_e32 v125, v127
	v_mov_b32_e32 v124, v127
	v_mov_b32_e32 v123, v127
	v_mov_b32_e32 v122, v127
	v_mov_b32_e32 v121, v127
	v_mov_b32_e32 v120, v127
	v_mov_b32_e32 v111, v127
	v_mov_b32_e32 v110, v127
	v_mov_b32_e32 v109, v127
	v_mov_b32_e32 v108, v127
	v_mov_b32_e32 v107, v127
	v_mov_b32_e32 v106, v127
	v_mov_b32_e32 v105, v127
	v_mov_b32_e32 v104, v127
	v_mov_b32_e32 v95, v127
	v_mov_b32_e32 v94, v127
	v_mov_b32_e32 v93, v127
	v_mov_b32_e32 v92, v127
	v_mov_b32_e32 v91, v127
	v_mov_b32_e32 v90, v127
	v_mov_b32_e32 v89, v127
	v_mov_b32_e32 v88, v127
	v_mov_b32_e32 v79, v127
	v_mov_b32_e32 v78, v127
	v_mov_b32_e32 v77, v127
	v_mov_b32_e32 v76, v127
	v_mov_b32_e32 v75, v127
	v_mov_b32_e32 v74, v127
	v_mov_b32_e32 v73, v127
	v_mov_b32_e32 v72, v127
	v_mov_b32_e32 v119, v127
	v_mov_b32_e32 v118, v127
	v_mov_b32_e32 v117, v127
	v_mov_b32_e32 v116, v127
	v_mov_b32_e32 v115, v127
	v_mov_b32_e32 v114, v127
	v_mov_b32_e32 v113, v127
	v_mov_b32_e32 v112, v127
	v_mov_b32_e32 v103, v127
	v_mov_b32_e32 v102, v127
	v_mov_b32_e32 v101, v127
	v_mov_b32_e32 v100, v127
	v_mov_b32_e32 v99, v127
	v_mov_b32_e32 v98, v127
	v_mov_b32_e32 v97, v127
	v_mov_b32_e32 v96, v127
	v_mov_b32_e32 v87, v127
	v_mov_b32_e32 v86, v127
	v_mov_b32_e32 v85, v127
	v_mov_b32_e32 v84, v127
	v_mov_b32_e32 v83, v127
	v_mov_b32_e32 v82, v127
	v_mov_b32_e32 v81, v127
	v_mov_b32_e32 v80, v127
	v_mov_b32_e32 v71, v127
	v_mov_b32_e32 v70, v127
	v_mov_b32_e32 v69, v127
	v_mov_b32_e32 v68, v127
	v_mov_b32_e32 v67, v127
	v_mov_b32_e32 v66, v127
	v_mov_b32_e32 v65, v127
	v_mov_b32_e32 v64, v127
	v_mov_b32_e32 v63, v127
	v_mov_b32_e32 v62, v127
	v_mov_b32_e32 v61, v127
	v_mov_b32_e32 v60, v127
	v_mov_b32_e32 v59, v127
	v_mov_b32_e32 v58, v127
	v_mov_b32_e32 v57, v127
	v_mov_b32_e32 v56, v127
	v_mov_b32_e32 v47, v127
	v_mov_b32_e32 v46, v127
	v_mov_b32_e32 v45, v127
	v_mov_b32_e32 v44, v127
	v_mov_b32_e32 v43, v127
	v_mov_b32_e32 v42, v127
	v_mov_b32_e32 v41, v127
	v_mov_b32_e32 v40, v127
	v_mov_b32_e32 v31, v127
	v_mov_b32_e32 v30, v127
	v_mov_b32_e32 v29, v127
	v_mov_b32_e32 v28, v127
	v_mov_b32_e32 v27, v127
	v_mov_b32_e32 v26, v127
	v_mov_b32_e32 v25, v127
	v_mov_b32_e32 v24, v127
	v_mov_b32_e32 v15, v127
	v_mov_b32_e32 v14, v127
	v_mov_b32_e32 v13, v127
	v_mov_b32_e32 v12, v127
	v_mov_b32_e32 v11, v127
	v_mov_b32_e32 v10, v127
	v_mov_b32_e32 v9, v127
	v_mov_b32_e32 v8, v127
	v_mov_b32_e32 v55, v127
	v_mov_b32_e32 v54, v127
	v_mov_b32_e32 v53, v127
	v_mov_b32_e32 v52, v127
	v_mov_b32_e32 v51, v127
	v_mov_b32_e32 v50, v127
	v_mov_b32_e32 v49, v127
	v_mov_b32_e32 v48, v127
	v_mov_b32_e32 v39, v127
	v_mov_b32_e32 v38, v127
	v_mov_b32_e32 v37, v127
	v_mov_b32_e32 v36, v127
	v_mov_b32_e32 v35, v127
	v_mov_b32_e32 v34, v127
	v_mov_b32_e32 v33, v127
	v_mov_b32_e32 v32, v127
	v_mov_b32_e32 v23, v127
	v_mov_b32_e32 v22, v127
	v_mov_b32_e32 v21, v127
	v_mov_b32_e32 v20, v127
	v_mov_b32_e32 v19, v127
	v_mov_b32_e32 v18, v127
	v_mov_b32_e32 v17, v127
	v_mov_b32_e32 v16, v127
	v_mov_b32_e32 v7, v127
	v_mov_b32_e32 v6, v127
	v_mov_b32_e32 v5, v127
	v_mov_b32_e32 v4, v127
	v_mov_b32_e32 v3, v127
	v_mov_b32_e32 v2, v127
	v_mov_b32_e32 v1, v127
	v_mov_b32_e32 v0, v127
	s_cbranch_vccnz .LBB0_746
	s_add_u32 s14, s14, 0x80
	s_addc_u32 s15, s15, 0
	s_add_u32 s64, s64, 0x100
	v_mov_b32_e32 v0, 0
	s_addc_u32 s65, s65, 0
	s_mov_b32 s16, 0
	v_mov_b32_e32 v1, v0
	v_mov_b32_e32 v2, v0
	v_mov_b32_e32 v3, v0
	v_mov_b32_e32 v4, v0
	v_mov_b32_e32 v5, v0
	v_mov_b32_e32 v6, v0
	v_mov_b32_e32 v7, v0
	v_mov_b32_e32 v16, v0
	v_mov_b32_e32 v17, v0
	v_mov_b32_e32 v18, v0
	v_mov_b32_e32 v19, v0
	v_mov_b32_e32 v20, v0
	v_mov_b32_e32 v21, v0
	v_mov_b32_e32 v22, v0
	v_mov_b32_e32 v23, v0
	v_mov_b32_e32 v32, v0
	v_mov_b32_e32 v33, v0
	v_mov_b32_e32 v34, v0
	v_mov_b32_e32 v35, v0
	v_mov_b32_e32 v36, v0
	v_mov_b32_e32 v37, v0
	v_mov_b32_e32 v38, v0
	v_mov_b32_e32 v39, v0
	v_mov_b32_e32 v48, v0
	v_mov_b32_e32 v49, v0
	v_mov_b32_e32 v50, v0
	v_mov_b32_e32 v51, v0
	v_mov_b32_e32 v52, v0
	v_mov_b32_e32 v53, v0
	v_mov_b32_e32 v54, v0
	v_mov_b32_e32 v55, v0
	v_mov_b32_e32 v8, v0
	v_mov_b32_e32 v9, v0
	v_mov_b32_e32 v10, v0
	v_mov_b32_e32 v11, v0
	v_mov_b32_e32 v12, v0
	v_mov_b32_e32 v13, v0
	v_mov_b32_e32 v14, v0
	v_mov_b32_e32 v15, v0
	v_mov_b32_e32 v24, v0
	v_mov_b32_e32 v25, v0
	v_mov_b32_e32 v26, v0
	v_mov_b32_e32 v27, v0
	v_mov_b32_e32 v28, v0
	v_mov_b32_e32 v29, v0
	v_mov_b32_e32 v30, v0
	v_mov_b32_e32 v31, v0
	v_mov_b32_e32 v40, v0
	v_mov_b32_e32 v41, v0
	v_mov_b32_e32 v42, v0
	v_mov_b32_e32 v43, v0
	v_mov_b32_e32 v44, v0
	v_mov_b32_e32 v45, v0
	v_mov_b32_e32 v46, v0
	v_mov_b32_e32 v47, v0
	v_mov_b32_e32 v56, v0
	v_mov_b32_e32 v57, v0
	v_mov_b32_e32 v58, v0
	v_mov_b32_e32 v59, v0
	v_mov_b32_e32 v60, v0
	v_mov_b32_e32 v61, v0
	v_mov_b32_e32 v62, v0
	v_mov_b32_e32 v63, v0
	v_mov_b32_e32 v64, v0
	v_mov_b32_e32 v65, v0
	v_mov_b32_e32 v66, v0
	v_mov_b32_e32 v67, v0
	v_mov_b32_e32 v68, v0
	v_mov_b32_e32 v69, v0
	v_mov_b32_e32 v70, v0
	v_mov_b32_e32 v71, v0
	v_mov_b32_e32 v80, v0
	v_mov_b32_e32 v81, v0
	v_mov_b32_e32 v82, v0
	v_mov_b32_e32 v83, v0
	v_mov_b32_e32 v84, v0
	v_mov_b32_e32 v85, v0
	v_mov_b32_e32 v86, v0
	v_mov_b32_e32 v87, v0
	v_mov_b32_e32 v96, v0
	v_mov_b32_e32 v97, v0
	v_mov_b32_e32 v98, v0
	v_mov_b32_e32 v99, v0
	v_mov_b32_e32 v100, v0
	v_mov_b32_e32 v101, v0
	v_mov_b32_e32 v102, v0
	v_mov_b32_e32 v103, v0
	v_mov_b32_e32 v112, v0
	v_mov_b32_e32 v113, v0
	v_mov_b32_e32 v114, v0
	v_mov_b32_e32 v115, v0
	v_mov_b32_e32 v116, v0
	v_mov_b32_e32 v117, v0
	v_mov_b32_e32 v118, v0
	v_mov_b32_e32 v119, v0
	v_mov_b32_e32 v72, v0
	v_mov_b32_e32 v73, v0
	v_mov_b32_e32 v74, v0
	v_mov_b32_e32 v75, v0
	v_mov_b32_e32 v76, v0
	v_mov_b32_e32 v77, v0
	v_mov_b32_e32 v78, v0
	v_mov_b32_e32 v79, v0
	v_mov_b32_e32 v88, v0
	v_mov_b32_e32 v89, v0
	v_mov_b32_e32 v90, v0
	v_mov_b32_e32 v91, v0
	v_mov_b32_e32 v92, v0
	v_mov_b32_e32 v93, v0
	v_mov_b32_e32 v94, v0
	v_mov_b32_e32 v95, v0
	v_mov_b32_e32 v104, v0
	v_mov_b32_e32 v105, v0
	v_mov_b32_e32 v106, v0
	v_mov_b32_e32 v107, v0
	v_mov_b32_e32 v108, v0
	v_mov_b32_e32 v109, v0
	v_mov_b32_e32 v110, v0
	v_mov_b32_e32 v111, v0
	v_mov_b32_e32 v120, v0
	v_mov_b32_e32 v121, v0
	v_mov_b32_e32 v122, v0
	v_mov_b32_e32 v123, v0
	v_mov_b32_e32 v124, v0
	v_mov_b32_e32 v125, v0
	v_mov_b32_e32 v126, v0
	v_mov_b32_e32 v127, v0
	.p2alignl 6, 3212836864

; template <class Epi>
; DEVI void gemm_phase(LAS unsigned char* lds, const bf16_t* gA, const bf16_t* gBt, const int lda, const int ldb, const int K, const StaticOrder S_, const Epi E) {
;     ...
;     for (;;) {
;         const bool has_next = S_.next(ui + 1, nxt);
;         const char* nA = has_next ? (const char*)gA + (size_t)nxt.pm * tstepA : cA; const char* nB = has_next ? (const char*)gBt + (size_t)nxt.pn * tstepB : cB;
;         for (int t = 0; t < nt; t += 2) {
;             const bool last = (t == nt - 2);
;             const char* a1 = cA + (size_t)(t + 1) * kstep;
;             const char* a2 = last ? nA : cA + (size_t)(t + 2) * kstep; const char* b2 = last ? nB : cB + (size_t)(t + 2) * kstep;
;     ...
;         for (int a = 0; a < 2; ++a)
; #pragma unroll
;             for (int b = 0; b < 2; ++b)
; #pragma unroll
;                 for (int m = 0; m < 4; ++m)
; #pragma unroll
;                     for (int n = 0; n < 2; ++n) acc[a][b][m][n] = (f32x4){0.f, 0.f, 0.f, 0.f};
.LBB0_1299:
	v_mov_b32_e32 v127, 0
	s_andn2_b64 vcc, exec, s[10:11]
	v_mov_b32_e32 v126, v127
	v_mov_b32_e32 v125, v127
	v_mov_b32_e32 v124, v127
	v_mov_b32_e32 v123, v127
	v_mov_b32_e32 v122, v127
	v_mov_b32_e32 v121, v127
	v_mov_b32_e32 v120, v127
	v_mov_b32_e32 v111, v127
	v_mov_b32_e32 v110, v127
	v_mov_b32_e32 v109, v127
	v_mov_b32_e32 v108, v127
	v_mov_b32_e32 v107, v127
	v_mov_b32_e32 v106, v127
	v_mov_b32_e32 v105, v127
	v_mov_b32_e32 v104, v127
	v_mov_b32_e32 v95, v127
	v_mov_b32_e32 v94, v127
	v_mov_b32_e32 v93, v127
	v_mov_b32_e32 v92, v127
	v_mov_b32_e32 v91, v127
	v_mov_b32_e32 v90, v127
	v_mov_b32_e32 v89, v127
	v_mov_b32_e32 v88, v127
	v_mov_b32_e32 v79, v127
	v_mov_b32_e32 v78, v127
	v_mov_b32_e32 v77, v127
	v_mov_b32_e32 v76, v127
	v_mov_b32_e32 v75, v127
	v_mov_b32_e32 v74, v127
	v_mov_b32_e32 v73, v127
	v_mov_b32_e32 v72, v127
	v_mov_b32_e32 v119, v127
	v_mov_b32_e32 v118, v127
	v_mov_b32_e32 v117, v127
	v_mov_b32_e32 v116, v127
	v_mov_b32_e32 v115, v127
	v_mov_b32_e32 v114, v127
	v_mov_b32_e32 v113, v127
	v_mov_b32_e32 v112, v127
	v_mov_b32_e32 v103, v127
	v_mov_b32_e32 v102, v127
	v_mov_b32_e32 v101, v127
	v_mov_b32_e32 v100, v127
	v_mov_b32_e32 v99, v127
	v_mov_b32_e32 v98, v127
	v_mov_b32_e32 v97, v127
	v_mov_b32_e32 v96, v127
	v_mov_b32_e32 v87, v127
	v_mov_b32_e32 v86, v127
	v_mov_b32_e32 v85, v127
	v_mov_b32_e32 v84, v127
	v_mov_b32_e32 v83, v127
	v_mov_b32_e32 v82, v127
	v_mov_b32_e32 v81, v127
	v_mov_b32_e32 v80, v127
	v_mov_b32_e32 v71, v127
	v_mov_b32_e32 v70, v127
	v_mov_b32_e32 v69, v127
	v_mov_b32_e32 v68, v127
	v_mov_b32_e32 v67, v127
	v_mov_b32_e32 v66, v127
	v_mov_b32_e32 v65, v127
	v_mov_b32_e32 v64, v127
	v_mov_b32_e32 v63, v127
	v_mov_b32_e32 v62, v127
	v_mov_b32_e32 v61, v127
	v_mov_b32_e32 v60, v127
	v_mov_b32_e32 v59, v127
	v_mov_b32_e32 v58, v127
	v_mov_b32_e32 v57, v127
	v_mov_b32_e32 v56, v127
	v_mov_b32_e32 v47, v127
	v_mov_b32_e32 v46, v127
	v_mov_b32_e32 v45, v127
	v_mov_b32_e32 v44, v127
	v_mov_b32_e32 v43, v127
	v_mov_b32_e32 v42, v127
	v_mov_b32_e32 v41, v127
	v_mov_b32_e32 v40, v127
	v_mov_b32_e32 v31, v127
	v_mov_b32_e32 v30, v127
	v_mov_b32_e32 v29, v127
	v_mov_b32_e32 v28, v127
	v_mov_b32_e32 v27, v127
	v_mov_b32_e32 v26, v127
	v_mov_b32_e32 v25, v127
	v_mov_b32_e32 v24, v127
	v_mov_b32_e32 v15, v127
	v_mov_b32_e32 v14, v127
	v_mov_b32_e32 v13, v127
	v_mov_b32_e32 v12, v127
	v_mov_b32_e32 v11, v127
	v_mov_b32_e32 v10, v127
	v_mov_b32_e32 v9, v127
	v_mov_b32_e32 v8, v127
	v_mov_b32_e32 v55, v127
	v_mov_b32_e32 v54, v127
	v_mov_b32_e32 v53, v127
	v_mov_b32_e32 v52, v127
	v_mov_b32_e32 v51, v127
	v_mov_b32_e32 v50, v127
	v_mov_b32_e32 v49, v127
	v_mov_b32_e32 v48, v127
	v_mov_b32_e32 v39, v127
	v_mov_b32_e32 v38, v127
	v_mov_b32_e32 v37, v127
	v_mov_b32_e32 v36, v127
	v_mov_b32_e32 v35, v127
	v_mov_b32_e32 v34, v127
	v_mov_b32_e32 v33, v127
	v_mov_b32_e32 v32, v127
	v_mov_b32_e32 v23, v127
	v_mov_b32_e32 v22, v127
	v_mov_b32_e32 v21, v127
	v_mov_b32_e32 v20, v127
	v_mov_b32_e32 v19, v127
	v_mov_b32_e32 v18, v127
	v_mov_b32_e32 v17, v127
	v_mov_b32_e32 v16, v127
	v_mov_b32_e32 v7, v127
	v_mov_b32_e32 v6, v127
	v_mov_b32_e32 v5, v127
	v_mov_b32_e32 v4, v127
	v_mov_b32_e32 v3, v127
	v_mov_b32_e32 v2, v127
	s_waitcnt lgkmcnt(0)
	v_mov_b32_e32 v1, v127
	v_mov_b32_e32 v0, v127
	s_cbranch_vccnz .LBB0_1302
	s_add_u32 s14, s14, 0x80
	s_addc_u32 s15, s15, 0
	s_add_u32 s70, s70, 0x100
	v_mov_b32_e32 v0, 0
	s_addc_u32 s71, s71, 0
	s_mov_b32 s16, 0
	v_mov_b32_e32 v1, v0
	v_mov_b32_e32 v2, v0
	v_mov_b32_e32 v3, v0
	v_mov_b32_e32 v4, v0
	v_mov_b32_e32 v5, v0
	v_mov_b32_e32 v6, v0
	v_mov_b32_e32 v7, v0
	v_mov_b32_e32 v16, v0
	v_mov_b32_e32 v17, v0
	v_mov_b32_e32 v18, v0
	v_mov_b32_e32 v19, v0
	v_mov_b32_e32 v20, v0
	v_mov_b32_e32 v21, v0
	v_mov_b32_e32 v22, v0
	v_mov_b32_e32 v23, v0
	v_mov_b32_e32 v32, v0
	v_mov_b32_e32 v33, v0
	v_mov_b32_e32 v34, v0
	v_mov_b32_e32 v35, v0
	v_mov_b32_e32 v36, v0
	v_mov_b32_e32 v37, v0
	v_mov_b32_e32 v38, v0
	v_mov_b32_e32 v39, v0
	v_mov_b32_e32 v48, v0
	v_mov_b32_e32 v49, v0
	v_mov_b32_e32 v50, v0
	v_mov_b32_e32 v51, v0
	v_mov_b32_e32 v52, v0
	v_mov_b32_e32 v53, v0
	v_mov_b32_e32 v54, v0
	v_mov_b32_e32 v55, v0
	v_mov_b32_e32 v8, v0
	v_mov_b32_e32 v9, v0
	v_mov_b32_e32 v10, v0
	v_mov_b32_e32 v11, v0
	v_mov_b32_e32 v12, v0
	v_mov_b32_e32 v13, v0
	v_mov_b32_e32 v14, v0
	v_mov_b32_e32 v15, v0
	v_mov_b32_e32 v24, v0
	v_mov_b32_e32 v25, v0
	v_mov_b32_e32 v26, v0
	v_mov_b32_e32 v27, v0
	v_mov_b32_e32 v28, v0
	v_mov_b32_e32 v29, v0
	v_mov_b32_e32 v30, v0
	v_mov_b32_e32 v31, v0
	v_mov_b32_e32 v40, v0
	v_mov_b32_e32 v41, v0
	v_mov_b32_e32 v42, v0
	v_mov_b32_e32 v43, v0
	v_mov_b32_e32 v44, v0
	v_mov_b32_e32 v45, v0
	v_mov_b32_e32 v46, v0
	v_mov_b32_e32 v47, v0
	v_mov_b32_e32 v56, v0
	v_mov_b32_e32 v57, v0
	v_mov_b32_e32 v58, v0
	v_mov_b32_e32 v59, v0
	v_mov_b32_e32 v60, v0
	v_mov_b32_e32 v61, v0
	v_mov_b32_e32 v62, v0
	v_mov_b32_e32 v63, v0
	v_mov_b32_e32 v64, v0
	v_mov_b32_e32 v65, v0
	v_mov_b32_e32 v66, v0
	v_mov_b32_e32 v67, v0
	v_mov_b32_e32 v68, v0
	v_mov_b32_e32 v69, v0
	v_mov_b32_e32 v70, v0
	v_mov_b32_e32 v71, v0
	v_mov_b32_e32 v80, v0
	v_mov_b32_e32 v81, v0
	v_mov_b32_e32 v82, v0
	v_mov_b32_e32 v83, v0
	v_mov_b32_e32 v84, v0
	v_mov_b32_e32 v85, v0
	v_mov_b32_e32 v86, v0
	v_mov_b32_e32 v87, v0
	v_mov_b32_e32 v96, v0
	v_mov_b32_e32 v97, v0
	v_mov_b32_e32 v98, v0
	v_mov_b32_e32 v99, v0
	v_mov_b32_e32 v100, v0
	v_mov_b32_e32 v101, v0
	v_mov_b32_e32 v102, v0
	v_mov_b32_e32 v103, v0
	v_mov_b32_e32 v112, v0
	v_mov_b32_e32 v113, v0
	v_mov_b32_e32 v114, v0
	v_mov_b32_e32 v115, v0
	v_mov_b32_e32 v116, v0
	v_mov_b32_e32 v117, v0
	v_mov_b32_e32 v118, v0
	v_mov_b32_e32 v119, v0
	v_mov_b32_e32 v72, v0
	v_mov_b32_e32 v73, v0
	v_mov_b32_e32 v74, v0
	v_mov_b32_e32 v75, v0
	v_mov_b32_e32 v76, v0
	v_mov_b32_e32 v77, v0
	v_mov_b32_e32 v78, v0
	v_mov_b32_e32 v79, v0
	v_mov_b32_e32 v88, v0
	v_mov_b32_e32 v89, v0
	v_mov_b32_e32 v90, v0
	v_mov_b32_e32 v91, v0
	v_mov_b32_e32 v92, v0
	v_mov_b32_e32 v93, v0
	v_mov_b32_e32 v94, v0
	v_mov_b32_e32 v95, v0
	v_mov_b32_e32 v104, v0
	v_mov_b32_e32 v105, v0
	v_mov_b32_e32 v106, v0
	v_mov_b32_e32 v107, v0
	v_mov_b32_e32 v108, v0
	v_mov_b32_e32 v109, v0
	v_mov_b32_e32 v110, v0
	v_mov_b32_e32 v111, v0
	v_mov_b32_e32 v120, v0
	v_mov_b32_e32 v121, v0
	v_mov_b32_e32 v122, v0
	v_mov_b32_e32 v123, v0
	v_mov_b32_e32 v124, v0
	v_mov_b32_e32 v125, v0
	v_mov_b32_e32 v126, v0
	v_mov_b32_e32 v127, v0
	.p2alignl 6, 3212836864

; template <class Epi>
; DEVI void gemm_phase(LAS unsigned char* lds, const bf16_t* gA, const bf16_t* gBt, const int lda, const int ldb, const int K, const StaticOrder S_, const Epi E) {
;     ...
;     for (;;) {
;         const bool has_next = S_.next(ui + 1, nxt);
;         const char* nA = has_next ? (const char*)gA + (size_t)nxt.pm * tstepA : cA; const char* nB = has_next ? (const char*)gBt + (size_t)nxt.pn * tstepB : cB;
;         for (int t = 0; t < nt; t += 2) {
;             const bool last = (t == nt - 2);
;             const char* a1 = cA + (size_t)(t + 1) * kstep;
;             const char* a2 = last ? nA : cA + (size_t)(t + 2) * kstep; const char* b2 = last ? nB : cB + (size_t)(t + 2) * kstep;
;     ...
;         for (int a = 0; a < 2; ++a)
; #pragma unroll
;             for (int b = 0; b < 2; ++b)
; #pragma unroll
;                 for (int m = 0; m < 4; ++m)
; #pragma unroll
;                     for (int n = 0; n < 2; ++n) acc[a][b][m][n] = (f32x4){0.f, 0.f, 0.f, 0.f};
.LBB0_1443:
	v_mov_b32_e32 v123, 0
	s_andn2_b64 vcc, exec, s[60:61]
	v_mov_b32_e32 v122, v123
	v_mov_b32_e32 v121, v123
	v_mov_b32_e32 v120, v123
	v_mov_b32_e32 v119, v123
	v_mov_b32_e32 v118, v123
	v_mov_b32_e32 v117, v123
	v_mov_b32_e32 v116, v123
	v_mov_b32_e32 v111, v123
	v_mov_b32_e32 v110, v123
	v_mov_b32_e32 v109, v123
	v_mov_b32_e32 v108, v123
	v_mov_b32_e32 v103, v123
	v_mov_b32_e32 v102, v123
	v_mov_b32_e32 v101, v123
	v_mov_b32_e32 v100, v123
	v_mov_b32_e32 v95, v123
	v_mov_b32_e32 v94, v123
	v_mov_b32_e32 v93, v123
	v_mov_b32_e32 v92, v123
	v_mov_b32_e32 v87, v123
	v_mov_b32_e32 v86, v123
	v_mov_b32_e32 v85, v123
	v_mov_b32_e32 v84, v123
	v_mov_b32_e32 v79, v123
	v_mov_b32_e32 v78, v123
	v_mov_b32_e32 v77, v123
	v_mov_b32_e32 v76, v123
	v_mov_b32_e32 v71, v123
	v_mov_b32_e32 v70, v123
	v_mov_b32_e32 v69, v123
	v_mov_b32_e32 v68, v123
	v_mov_b32_e32 v127, v123
	v_mov_b32_e32 v126, v123
	v_mov_b32_e32 v125, v123
	v_mov_b32_e32 v124, v123
	v_mov_b32_e32 v115, v123
	v_mov_b32_e32 v114, v123
	v_mov_b32_e32 v113, v123
	v_mov_b32_e32 v112, v123
	v_mov_b32_e32 v107, v123
	v_mov_b32_e32 v106, v123
	v_mov_b32_e32 v105, v123
	v_mov_b32_e32 v104, v123
	v_mov_b32_e32 v99, v123
	v_mov_b32_e32 v98, v123
	v_mov_b32_e32 v97, v123
	v_mov_b32_e32 v96, v123
	v_mov_b32_e32 v91, v123
	v_mov_b32_e32 v90, v123
	v_mov_b32_e32 v89, v123
	v_mov_b32_e32 v88, v123
	v_mov_b32_e32 v83, v123
	v_mov_b32_e32 v82, v123
	v_mov_b32_e32 v81, v123
	v_mov_b32_e32 v80, v123
	v_mov_b32_e32 v75, v123
	v_mov_b32_e32 v74, v123
	v_mov_b32_e32 v73, v123
	v_mov_b32_e32 v72, v123
	v_mov_b32_e32 v67, v123
	v_mov_b32_e32 v66, v123
	v_mov_b32_e32 v65, v123
	v_mov_b32_e32 v64, v123
	v_mov_b32_e32 v63, v123
	v_mov_b32_e32 v62, v123
	v_mov_b32_e32 v61, v123
	v_mov_b32_e32 v60, v123
	v_mov_b32_e32 v59, v123
	v_mov_b32_e32 v58, v123
	v_mov_b32_e32 v57, v123
	v_mov_b32_e32 v56, v123
	v_mov_b32_e32 v47, v123
	v_mov_b32_e32 v46, v123
	v_mov_b32_e32 v45, v123
	v_mov_b32_e32 v44, v123
	v_mov_b32_e32 v43, v123
	v_mov_b32_e32 v42, v123
	v_mov_b32_e32 v41, v123
	v_mov_b32_e32 v40, v123
	v_mov_b32_e32 v31, v123
	v_mov_b32_e32 v30, v123
	v_mov_b32_e32 v29, v123
	v_mov_b32_e32 v28, v123
	v_mov_b32_e32 v27, v123
	v_mov_b32_e32 v26, v123
	v_mov_b32_e32 v25, v123
	v_mov_b32_e32 v24, v123
	v_mov_b32_e32 v15, v123
	v_mov_b32_e32 v14, v123
	v_mov_b32_e32 v13, v123
	v_mov_b32_e32 v12, v123
	v_mov_b32_e32 v11, v123
	v_mov_b32_e32 v10, v123
	v_mov_b32_e32 v9, v123
	v_mov_b32_e32 v8, v123
	v_mov_b32_e32 v55, v123
	v_mov_b32_e32 v54, v123
	v_mov_b32_e32 v53, v123
	v_mov_b32_e32 v52, v123
	v_mov_b32_e32 v51, v123
	v_mov_b32_e32 v50, v123
	v_mov_b32_e32 v49, v123
	v_mov_b32_e32 v48, v123
	v_mov_b32_e32 v39, v123
	v_mov_b32_e32 v38, v123
	v_mov_b32_e32 v37, v123
	v_mov_b32_e32 v36, v123
	v_mov_b32_e32 v35, v123
	v_mov_b32_e32 v34, v123
	v_mov_b32_e32 v33, v123
	v_mov_b32_e32 v32, v123
	v_mov_b32_e32 v23, v123
	v_mov_b32_e32 v22, v123
	v_mov_b32_e32 v21, v123
	v_mov_b32_e32 v20, v123
	v_mov_b32_e32 v19, v123
	v_mov_b32_e32 v18, v123
	v_mov_b32_e32 v17, v123
	v_mov_b32_e32 v16, v123
	v_mov_b32_e32 v7, v123
	v_mov_b32_e32 v6, v123
	v_mov_b32_e32 v5, v123
	v_mov_b32_e32 v4, v123
	v_mov_b32_e32 v3, v123
	v_mov_b32_e32 v2, v123
	v_mov_b32_e32 v1, v123
	v_mov_b32_e32 v0, v123
	s_cbranch_vccnz .LBB0_1446
	s_add_u32 s14, s14, 0x80
	s_addc_u32 s15, s15, 0
	s_add_u32 s77, s70, 0x100
	v_mov_b32_e32 v0, 0
	s_addc_u32 s78, s71, 0
	s_mov_b32 s16, 0
	v_mov_b32_e32 v1, v0
	v_mov_b32_e32 v2, v0
	v_mov_b32_e32 v3, v0
	v_mov_b32_e32 v4, v0
	v_mov_b32_e32 v5, v0
	v_mov_b32_e32 v6, v0
	v_mov_b32_e32 v7, v0
	v_mov_b32_e32 v16, v0
	v_mov_b32_e32 v17, v0
	v_mov_b32_e32 v18, v0
	v_mov_b32_e32 v19, v0
	v_mov_b32_e32 v20, v0
	v_mov_b32_e32 v21, v0
	v_mov_b32_e32 v22, v0
	v_mov_b32_e32 v23, v0
	v_mov_b32_e32 v32, v0
	v_mov_b32_e32 v33, v0
	v_mov_b32_e32 v34, v0
	v_mov_b32_e32 v35, v0
	v_mov_b32_e32 v36, v0
	v_mov_b32_e32 v37, v0
	v_mov_b32_e32 v38, v0
	v_mov_b32_e32 v39, v0
	v_mov_b32_e32 v48, v0
	v_mov_b32_e32 v49, v0
	v_mov_b32_e32 v50, v0
	v_mov_b32_e32 v51, v0
	v_mov_b32_e32 v52, v0
	v_mov_b32_e32 v53, v0
	v_mov_b32_e32 v54, v0
	v_mov_b32_e32 v55, v0
	v_mov_b32_e32 v8, v0
	v_mov_b32_e32 v9, v0
	v_mov_b32_e32 v10, v0
	v_mov_b32_e32 v11, v0
	v_mov_b32_e32 v12, v0
	v_mov_b32_e32 v13, v0
	v_mov_b32_e32 v14, v0
	v_mov_b32_e32 v15, v0
	v_mov_b32_e32 v24, v0
	v_mov_b32_e32 v25, v0
	v_mov_b32_e32 v26, v0
	v_mov_b32_e32 v27, v0
	v_mov_b32_e32 v28, v0
	v_mov_b32_e32 v29, v0
	v_mov_b32_e32 v30, v0
	v_mov_b32_e32 v31, v0
	v_mov_b32_e32 v40, v0
	v_mov_b32_e32 v41, v0
	v_mov_b32_e32 v42, v0
	v_mov_b32_e32 v43, v0
	v_mov_b32_e32 v44, v0
	v_mov_b32_e32 v45, v0
	v_mov_b32_e32 v46, v0
	v_mov_b32_e32 v47, v0
	v_mov_b32_e32 v56, v0
	v_mov_b32_e32 v57, v0
	v_mov_b32_e32 v58, v0
	v_mov_b32_e32 v59, v0
	v_mov_b32_e32 v60, v0
	v_mov_b32_e32 v61, v0
	v_mov_b32_e32 v62, v0
	v_mov_b32_e32 v63, v0
	v_mov_b32_e32 v64, v0
	v_mov_b32_e32 v65, v0
	v_mov_b32_e32 v66, v0
	v_mov_b32_e32 v67, v0
	v_mov_b32_e32 v72, v0
	v_mov_b32_e32 v73, v0
	v_mov_b32_e32 v74, v0
	v_mov_b32_e32 v75, v0
	v_mov_b32_e32 v80, v0
	v_mov_b32_e32 v81, v0
	v_mov_b32_e32 v82, v0
	v_mov_b32_e32 v83, v0
	v_mov_b32_e32 v88, v0
	v_mov_b32_e32 v89, v0
	v_mov_b32_e32 v90, v0
	v_mov_b32_e32 v91, v0
	v_mov_b32_e32 v96, v0
	v_mov_b32_e32 v97, v0
	v_mov_b32_e32 v98, v0
	v_mov_b32_e32 v99, v0
	v_mov_b32_e32 v104, v0
	v_mov_b32_e32 v105, v0
	v_mov_b32_e32 v106, v0
	v_mov_b32_e32 v107, v0
	v_mov_b32_e32 v112, v0
	v_mov_b32_e32 v113, v0
	v_mov_b32_e32 v114, v0
	v_mov_b32_e32 v115, v0
	v_mov_b32_e32 v124, v0
	v_mov_b32_e32 v125, v0
	v_mov_b32_e32 v126, v0
	v_mov_b32_e32 v127, v0
	v_mov_b32_e32 v68, v0
	v_mov_b32_e32 v69, v0
	v_mov_b32_e32 v70, v0
	v_mov_b32_e32 v71, v0
	v_mov_b32_e32 v76, v0
	v_mov_b32_e32 v77, v0
	v_mov_b32_e32 v78, v0
	v_mov_b32_e32 v79, v0
	v_mov_b32_e32 v84, v0
	v_mov_b32_e32 v85, v0
	v_mov_b32_e32 v86, v0
	v_mov_b32_e32 v87, v0
	v_mov_b32_e32 v92, v0
	v_mov_b32_e32 v93, v0
	v_mov_b32_e32 v94, v0
	v_mov_b32_e32 v95, v0
	v_mov_b32_e32 v100, v0
	v_mov_b32_e32 v101, v0
	v_mov_b32_e32 v102, v0
	v_mov_b32_e32 v103, v0
	v_mov_b32_e32 v108, v0
	v_mov_b32_e32 v109, v0
	v_mov_b32_e32 v110, v0
	v_mov_b32_e32 v111, v0
	v_mov_b32_e32 v116, v0
	v_mov_b32_e32 v117, v0
	v_mov_b32_e32 v118, v0
	v_mov_b32_e32 v119, v0
	v_mov_b32_e32 v120, v0
	v_mov_b32_e32 v121, v0
	v_mov_b32_e32 v122, v0
	v_mov_b32_e32 v123, v0
	.p2alignl 6, 3212836864

; template <class Epi>
; DEVI void gemm_phase(LAS unsigned char* lds, const bf16_t* gA, const bf16_t* gBt, const int lda, const int ldb, const int K, const StaticOrder S_, const Epi E) {
;     ...
;     for (;;) {
;         const bool has_next = S_.next(ui + 1, nxt);
;         const char* nA = has_next ? (const char*)gA + (size_t)nxt.pm * tstepA : cA; const char* nB = has_next ? (const char*)gBt + (size_t)nxt.pn * tstepB : cB;
;         for (int t = 0; t < nt; t += 2) {
;             const bool last = (t == nt - 2);
;             const char* a1 = cA + (size_t)(t + 1) * kstep;
;             const char* a2 = last ? nA : cA + (size_t)(t + 2) * kstep; const char* b2 = last ? nB : cB + (size_t)(t + 2) * kstep;
;     ...
;         for (int a = 0; a < 2; ++a)
; #pragma unroll
;             for (int b = 0; b < 2; ++b)
; #pragma unroll
;                 for (int m = 0; m < 4; ++m)
; #pragma unroll
;                     for (int n = 0; n < 2; ++n) acc[a][b][m][n] = (f32x4){0.f, 0.f, 0.f, 0.f};
.LBB0_1846:
	v_mov_b32_e32 v127, 0
	s_andn2_b64 vcc, exec, s[10:11]
	v_mov_b32_e32 v126, v127
	v_mov_b32_e32 v125, v127
	v_mov_b32_e32 v124, v127
	v_mov_b32_e32 v123, v127
	v_mov_b32_e32 v122, v127
	v_mov_b32_e32 v121, v127
	v_mov_b32_e32 v120, v127
	v_mov_b32_e32 v111, v127
	v_mov_b32_e32 v110, v127
	v_mov_b32_e32 v109, v127
	v_mov_b32_e32 v108, v127
	v_mov_b32_e32 v107, v127
	v_mov_b32_e32 v106, v127
	v_mov_b32_e32 v105, v127
	v_mov_b32_e32 v104, v127
	v_mov_b32_e32 v95, v127
	v_mov_b32_e32 v94, v127
	v_mov_b32_e32 v93, v127
	v_mov_b32_e32 v92, v127
	v_mov_b32_e32 v91, v127
	v_mov_b32_e32 v90, v127
	v_mov_b32_e32 v89, v127
	v_mov_b32_e32 v88, v127
	v_mov_b32_e32 v79, v127
	v_mov_b32_e32 v78, v127
	v_mov_b32_e32 v77, v127
	v_mov_b32_e32 v76, v127
	v_mov_b32_e32 v75, v127
	v_mov_b32_e32 v74, v127
	v_mov_b32_e32 v73, v127
	v_mov_b32_e32 v72, v127
	v_mov_b32_e32 v119, v127
	v_mov_b32_e32 v118, v127
	v_mov_b32_e32 v117, v127
	v_mov_b32_e32 v116, v127
	v_mov_b32_e32 v115, v127
	v_mov_b32_e32 v114, v127
	v_mov_b32_e32 v113, v127
	v_mov_b32_e32 v112, v127
	v_mov_b32_e32 v103, v127
	v_mov_b32_e32 v102, v127
	v_mov_b32_e32 v101, v127
	v_mov_b32_e32 v100, v127
	v_mov_b32_e32 v99, v127
	v_mov_b32_e32 v98, v127
	v_mov_b32_e32 v97, v127
	v_mov_b32_e32 v96, v127
	v_mov_b32_e32 v87, v127
	v_mov_b32_e32 v86, v127
	v_mov_b32_e32 v85, v127
	v_mov_b32_e32 v84, v127
	v_mov_b32_e32 v83, v127
	v_mov_b32_e32 v82, v127
	v_mov_b32_e32 v81, v127
	v_mov_b32_e32 v80, v127
	v_mov_b32_e32 v71, v127
	v_mov_b32_e32 v70, v127
	v_mov_b32_e32 v69, v127
	v_mov_b32_e32 v68, v127
	v_mov_b32_e32 v67, v127
	v_mov_b32_e32 v66, v127
	v_mov_b32_e32 v65, v127
	v_mov_b32_e32 v64, v127
	v_mov_b32_e32 v63, v127
	v_mov_b32_e32 v62, v127
	v_mov_b32_e32 v61, v127
	v_mov_b32_e32 v60, v127
	v_mov_b32_e32 v59, v127
	v_mov_b32_e32 v58, v127
	v_mov_b32_e32 v57, v127
	v_mov_b32_e32 v56, v127
	v_mov_b32_e32 v47, v127
	v_mov_b32_e32 v46, v127
	v_mov_b32_e32 v45, v127
	v_mov_b32_e32 v44, v127
	v_mov_b32_e32 v43, v127
	v_mov_b32_e32 v42, v127
	v_mov_b32_e32 v41, v127
	v_mov_b32_e32 v40, v127
	v_mov_b32_e32 v31, v127
	v_mov_b32_e32 v30, v127
	v_mov_b32_e32 v29, v127
	v_mov_b32_e32 v28, v127
	v_mov_b32_e32 v27, v127
	v_mov_b32_e32 v26, v127
	v_mov_b32_e32 v25, v127
	v_mov_b32_e32 v24, v127
	v_mov_b32_e32 v15, v127
	v_mov_b32_e32 v14, v127
	v_mov_b32_e32 v13, v127
	v_mov_b32_e32 v12, v127
	v_mov_b32_e32 v11, v127
	v_mov_b32_e32 v10, v127
	v_mov_b32_e32 v9, v127
	v_mov_b32_e32 v8, v127
	v_mov_b32_e32 v55, v127
	v_mov_b32_e32 v54, v127
	v_mov_b32_e32 v53, v127
	v_mov_b32_e32 v52, v127
	v_mov_b32_e32 v51, v127
	v_mov_b32_e32 v50, v127
	v_mov_b32_e32 v49, v127
	v_mov_b32_e32 v48, v127
	v_mov_b32_e32 v39, v127
	v_mov_b32_e32 v38, v127
	v_mov_b32_e32 v37, v127
	v_mov_b32_e32 v36, v127
	v_mov_b32_e32 v35, v127
	v_mov_b32_e32 v34, v127
	v_mov_b32_e32 v33, v127
	v_mov_b32_e32 v32, v127
	v_mov_b32_e32 v23, v127
	v_mov_b32_e32 v22, v127
	v_mov_b32_e32 v21, v127
	v_mov_b32_e32 v20, v127
	v_mov_b32_e32 v19, v127
	v_mov_b32_e32 v18, v127
	v_mov_b32_e32 v17, v127
	v_mov_b32_e32 v16, v127
	v_mov_b32_e32 v7, v127
	v_mov_b32_e32 v6, v127
	v_mov_b32_e32 v5, v127
	v_mov_b32_e32 v4, v127
	v_mov_b32_e32 v3, v127
	v_mov_b32_e32 v2, v127
	s_waitcnt lgkmcnt(0)
	v_mov_b32_e32 v1, v127
	v_mov_b32_e32 v0, v127
	s_cbranch_vccnz .LBB0_1850
	s_add_u32 s14, s14, 0x80
	s_addc_u32 s15, s15, 0
	s_add_u32 s56, s56, 0x100
	v_mov_b32_e32 v0, 0
	s_addc_u32 s57, s57, 0
	s_mov_b32 s16, 0
	v_mov_b32_e32 v1, v0
	v_mov_b32_e32 v2, v0
	v_mov_b32_e32 v3, v0
	v_mov_b32_e32 v4, v0
	v_mov_b32_e32 v5, v0
	v_mov_b32_e32 v6, v0
	v_mov_b32_e32 v7, v0
	v_mov_b32_e32 v16, v0
	v_mov_b32_e32 v17, v0
	v_mov_b32_e32 v18, v0
	v_mov_b32_e32 v19, v0
	v_mov_b32_e32 v20, v0
	v_mov_b32_e32 v21, v0
	v_mov_b32_e32 v22, v0
	v_mov_b32_e32 v23, v0
	v_mov_b32_e32 v32, v0
	v_mov_b32_e32 v33, v0
	v_mov_b32_e32 v34, v0
	v_mov_b32_e32 v35, v0
	v_mov_b32_e32 v36, v0
	v_mov_b32_e32 v37, v0
	v_mov_b32_e32 v38, v0
	v_mov_b32_e32 v39, v0
	v_mov_b32_e32 v48, v0
	v_mov_b32_e32 v49, v0
	v_mov_b32_e32 v50, v0
	v_mov_b32_e32 v51, v0
	v_mov_b32_e32 v52, v0
	v_mov_b32_e32 v53, v0
	v_mov_b32_e32 v54, v0
	v_mov_b32_e32 v55, v0
	v_mov_b32_e32 v8, v0
	v_mov_b32_e32 v9, v0
	v_mov_b32_e32 v10, v0
	v_mov_b32_e32 v11, v0
	v_mov_b32_e32 v12, v0
	v_mov_b32_e32 v13, v0
	v_mov_b32_e32 v14, v0
	v_mov_b32_e32 v15, v0
	v_mov_b32_e32 v24, v0
	v_mov_b32_e32 v25, v0
	v_mov_b32_e32 v26, v0
	v_mov_b32_e32 v27, v0
	v_mov_b32_e32 v28, v0
	v_mov_b32_e32 v29, v0
	v_mov_b32_e32 v30, v0
	v_mov_b32_e32 v31, v0
	v_mov_b32_e32 v40, v0
	v_mov_b32_e32 v41, v0
	v_mov_b32_e32 v42, v0
	v_mov_b32_e32 v43, v0
	v_mov_b32_e32 v44, v0
	v_mov_b32_e32 v45, v0
	v_mov_b32_e32 v46, v0
	v_mov_b32_e32 v47, v0
	v_mov_b32_e32 v56, v0
	v_mov_b32_e32 v57, v0
	v_mov_b32_e32 v58, v0
	v_mov_b32_e32 v59, v0
	v_mov_b32_e32 v60, v0
	v_mov_b32_e32 v61, v0
	v_mov_b32_e32 v62, v0
	v_mov_b32_e32 v63, v0
	v_mov_b32_e32 v64, v0
	v_mov_b32_e32 v65, v0
	v_mov_b32_e32 v66, v0
	v_mov_b32_e32 v67, v0
	v_mov_b32_e32 v68, v0
	v_mov_b32_e32 v69, v0
	v_mov_b32_e32 v70, v0
	v_mov_b32_e32 v71, v0
	v_mov_b32_e32 v80, v0
	v_mov_b32_e32 v81, v0
	v_mov_b32_e32 v82, v0
	v_mov_b32_e32 v83, v0
	v_mov_b32_e32 v84, v0
	v_mov_b32_e32 v85, v0
	v_mov_b32_e32 v86, v0
	v_mov_b32_e32 v87, v0
	v_mov_b32_e32 v96, v0
	v_mov_b32_e32 v97, v0
	v_mov_b32_e32 v98, v0
	v_mov_b32_e32 v99, v0
	v_mov_b32_e32 v100, v0
	v_mov_b32_e32 v101, v0
	v_mov_b32_e32 v102, v0
	v_mov_b32_e32 v103, v0
	v_mov_b32_e32 v112, v0
	v_mov_b32_e32 v113, v0
	v_mov_b32_e32 v114, v0
	v_mov_b32_e32 v115, v0
	v_mov_b32_e32 v116, v0
	v_mov_b32_e32 v117, v0
	v_mov_b32_e32 v118, v0
	v_mov_b32_e32 v119, v0
	v_mov_b32_e32 v72, v0
	v_mov_b32_e32 v73, v0
	v_mov_b32_e32 v74, v0
	v_mov_b32_e32 v75, v0
	v_mov_b32_e32 v76, v0
	v_mov_b32_e32 v77, v0
	v_mov_b32_e32 v78, v0
	v_mov_b32_e32 v79, v0
	v_mov_b32_e32 v88, v0
	v_mov_b32_e32 v89, v0
	v_mov_b32_e32 v90, v0
	v_mov_b32_e32 v91, v0
	v_mov_b32_e32 v92, v0
	v_mov_b32_e32 v93, v0
	v_mov_b32_e32 v94, v0
	v_mov_b32_e32 v95, v0
	v_mov_b32_e32 v104, v0
	v_mov_b32_e32 v105, v0
	v_mov_b32_e32 v106, v0
	v_mov_b32_e32 v107, v0
	v_mov_b32_e32 v108, v0
	v_mov_b32_e32 v109, v0
	v_mov_b32_e32 v110, v0
	v_mov_b32_e32 v111, v0
	v_mov_b32_e32 v120, v0
	v_mov_b32_e32 v121, v0
	v_mov_b32_e32 v122, v0
	v_mov_b32_e32 v123, v0
	v_mov_b32_e32 v124, v0
	v_mov_b32_e32 v125, v0
	v_mov_b32_e32 v126, v0
	v_mov_b32_e32 v127, v0
	.p2alignl 6, 3212836864

; template <class Epi>
; DEVI void gemm_phase(LAS unsigned char* lds, const bf16_t* gA, const bf16_t* gBt, const int lda, const int ldb, const int K, const StaticOrder S_, const Epi E) {
;     ...
;     for (;;) {
;         const bool has_next = S_.next(ui + 1, nxt);
;         const char* nA = has_next ? (const char*)gA + (size_t)nxt.pm * tstepA : cA; const char* nB = has_next ? (const char*)gBt + (size_t)nxt.pn * tstepB : cB;
;         for (int t = 0; t < nt; t += 2) {
;             const bool last = (t == nt - 2);
;             const char* a1 = cA + (size_t)(t + 1) * kstep;
;             const char* a2 = last ? nA : cA + (size_t)(t + 2) * kstep; const char* b2 = last ? nB : cB + (size_t)(t + 2) * kstep;
;     ...
;         for (int a = 0; a < 2; ++a)
; #pragma unroll
;             for (int b = 0; b < 2; ++b)
; #pragma unroll
;                 for (int m = 0; m < 4; ++m)
; #pragma unroll
;                     for (int n = 0; n < 2; ++n) acc[a][b][m][n] = (f32x4){0.f, 0.f, 0.f, 0.f};
.LBB0_1978:
	v_mov_b32_e32 v127, 0
	s_andn2_b64 vcc, exec, s[42:43]
	v_mov_b32_e32 v126, v127
	v_mov_b32_e32 v125, v127
	v_mov_b32_e32 v124, v127
	v_mov_b32_e32 v123, v127
	v_mov_b32_e32 v122, v127
	v_mov_b32_e32 v121, v127
	v_mov_b32_e32 v120, v127
	v_mov_b32_e32 v111, v127
	v_mov_b32_e32 v110, v127
	v_mov_b32_e32 v109, v127
	v_mov_b32_e32 v108, v127
	v_mov_b32_e32 v107, v127
	v_mov_b32_e32 v106, v127
	v_mov_b32_e32 v105, v127
	v_mov_b32_e32 v104, v127
	v_mov_b32_e32 v95, v127
	v_mov_b32_e32 v94, v127
	v_mov_b32_e32 v93, v127
	v_mov_b32_e32 v92, v127
	v_mov_b32_e32 v91, v127
	v_mov_b32_e32 v90, v127
	v_mov_b32_e32 v89, v127
	v_mov_b32_e32 v88, v127
	v_mov_b32_e32 v79, v127
	v_mov_b32_e32 v78, v127
	v_mov_b32_e32 v77, v127
	v_mov_b32_e32 v76, v127
	v_mov_b32_e32 v75, v127
	v_mov_b32_e32 v74, v127
	v_mov_b32_e32 v73, v127
	v_mov_b32_e32 v72, v127
	v_mov_b32_e32 v119, v127
	v_mov_b32_e32 v118, v127
	v_mov_b32_e32 v117, v127
	v_mov_b32_e32 v116, v127
	v_mov_b32_e32 v115, v127
	v_mov_b32_e32 v114, v127
	v_mov_b32_e32 v113, v127
	v_mov_b32_e32 v112, v127
	v_mov_b32_e32 v103, v127
	v_mov_b32_e32 v102, v127
	v_mov_b32_e32 v101, v127
	v_mov_b32_e32 v100, v127
	v_mov_b32_e32 v99, v127
	v_mov_b32_e32 v98, v127
	v_mov_b32_e32 v97, v127
	v_mov_b32_e32 v96, v127
	v_mov_b32_e32 v87, v127
	v_mov_b32_e32 v86, v127
	v_mov_b32_e32 v85, v127
	v_mov_b32_e32 v84, v127
	v_mov_b32_e32 v83, v127
	v_mov_b32_e32 v82, v127
	v_mov_b32_e32 v81, v127
	v_mov_b32_e32 v80, v127
	v_mov_b32_e32 v71, v127
	v_mov_b32_e32 v70, v127
	v_mov_b32_e32 v69, v127
	v_mov_b32_e32 v68, v127
	v_mov_b32_e32 v67, v127
	v_mov_b32_e32 v66, v127
	v_mov_b32_e32 v65, v127
	v_mov_b32_e32 v64, v127
	v_mov_b32_e32 v63, v127
	v_mov_b32_e32 v62, v127
	v_mov_b32_e32 v61, v127
	v_mov_b32_e32 v60, v127
	v_mov_b32_e32 v59, v127
	v_mov_b32_e32 v58, v127
	v_mov_b32_e32 v57, v127
	v_mov_b32_e32 v56, v127
	v_mov_b32_e32 v47, v127
	v_mov_b32_e32 v46, v127
	v_mov_b32_e32 v45, v127
	v_mov_b32_e32 v44, v127
	v_mov_b32_e32 v43, v127
	v_mov_b32_e32 v42, v127
	v_mov_b32_e32 v41, v127
	v_mov_b32_e32 v40, v127
	v_mov_b32_e32 v31, v127
	v_mov_b32_e32 v30, v127
	v_mov_b32_e32 v29, v127
	v_mov_b32_e32 v28, v127
	v_mov_b32_e32 v27, v127
	v_mov_b32_e32 v26, v127
	v_mov_b32_e32 v25, v127
	v_mov_b32_e32 v24, v127
	v_mov_b32_e32 v15, v127
	v_mov_b32_e32 v14, v127
	v_mov_b32_e32 v13, v127
	v_mov_b32_e32 v12, v127
	v_mov_b32_e32 v11, v127
	v_mov_b32_e32 v10, v127
	v_mov_b32_e32 v9, v127
	v_mov_b32_e32 v8, v127
	v_mov_b32_e32 v55, v127
	v_mov_b32_e32 v54, v127
	v_mov_b32_e32 v53, v127
	v_mov_b32_e32 v52, v127
	v_mov_b32_e32 v51, v127
	v_mov_b32_e32 v50, v127
	v_mov_b32_e32 v49, v127
	v_mov_b32_e32 v48, v127
	v_mov_b32_e32 v39, v127
	v_mov_b32_e32 v38, v127
	v_mov_b32_e32 v37, v127
	v_mov_b32_e32 v36, v127
	v_mov_b32_e32 v35, v127
	v_mov_b32_e32 v34, v127
	v_mov_b32_e32 v33, v127
	v_mov_b32_e32 v32, v127
	v_mov_b32_e32 v23, v127
	v_mov_b32_e32 v22, v127
	v_mov_b32_e32 v21, v127
	v_mov_b32_e32 v20, v127
	v_mov_b32_e32 v19, v127
	v_mov_b32_e32 v18, v127
	v_mov_b32_e32 v17, v127
	v_mov_b32_e32 v16, v127
	v_mov_b32_e32 v7, v127
	v_mov_b32_e32 v6, v127
	v_mov_b32_e32 v5, v127
	v_mov_b32_e32 v4, v127
	v_mov_b32_e32 v3, v127
	v_mov_b32_e32 v2, v127
	v_mov_b32_e32 v1, v127
	v_mov_b32_e32 v0, v127
	s_cbranch_vccnz .LBB0_1981
	s_add_u32 s14, s14, 0x80
	s_addc_u32 s15, s15, 0
	s_add_u32 s60, s60, 0x100
	v_mov_b32_e32 v0, 0
	s_addc_u32 s61, s61, 0
	s_mov_b32 s16, 0
	v_mov_b32_e32 v1, v0
	v_mov_b32_e32 v2, v0
	v_mov_b32_e32 v3, v0
	v_mov_b32_e32 v4, v0
	v_mov_b32_e32 v5, v0
	v_mov_b32_e32 v6, v0
	v_mov_b32_e32 v7, v0
	v_mov_b32_e32 v16, v0
	v_mov_b32_e32 v17, v0
	v_mov_b32_e32 v18, v0
	v_mov_b32_e32 v19, v0
	v_mov_b32_e32 v20, v0
	v_mov_b32_e32 v21, v0
	v_mov_b32_e32 v22, v0
	v_mov_b32_e32 v23, v0
	v_mov_b32_e32 v32, v0
	v_mov_b32_e32 v33, v0
	v_mov_b32_e32 v34, v0
	v_mov_b32_e32 v35, v0
	v_mov_b32_e32 v36, v0
	v_mov_b32_e32 v37, v0
	v_mov_b32_e32 v38, v0
	v_mov_b32_e32 v39, v0
	v_mov_b32_e32 v48, v0
	v_mov_b32_e32 v49, v0
	v_mov_b32_e32 v50, v0
	v_mov_b32_e32 v51, v0
	v_mov_b32_e32 v52, v0
	v_mov_b32_e32 v53, v0
	v_mov_b32_e32 v54, v0
	v_mov_b32_e32 v55, v0
	v_mov_b32_e32 v8, v0
	v_mov_b32_e32 v9, v0
	v_mov_b32_e32 v10, v0
	v_mov_b32_e32 v11, v0
	v_mov_b32_e32 v12, v0
	v_mov_b32_e32 v13, v0
	v_mov_b32_e32 v14, v0
	v_mov_b32_e32 v15, v0
	v_mov_b32_e32 v24, v0
	v_mov_b32_e32 v25, v0
	v_mov_b32_e32 v26, v0
	v_mov_b32_e32 v27, v0
	v_mov_b32_e32 v28, v0
	v_mov_b32_e32 v29, v0
	v_mov_b32_e32 v30, v0
	v_mov_b32_e32 v31, v0
	v_mov_b32_e32 v40, v0
	v_mov_b32_e32 v41, v0
	v_mov_b32_e32 v42, v0
	v_mov_b32_e32 v43, v0
	v_mov_b32_e32 v44, v0
	v_mov_b32_e32 v45, v0
	v_mov_b32_e32 v46, v0
	v_mov_b32_e32 v47, v0
	v_mov_b32_e32 v56, v0
	v_mov_b32_e32 v57, v0
	v_mov_b32_e32 v58, v0
	v_mov_b32_e32 v59, v0
	v_mov_b32_e32 v60, v0
	v_mov_b32_e32 v61, v0
	v_mov_b32_e32 v62, v0
	v_mov_b32_e32 v63, v0
	v_mov_b32_e32 v64, v0
	v_mov_b32_e32 v65, v0
	v_mov_b32_e32 v66, v0
	v_mov_b32_e32 v67, v0
	v_mov_b32_e32 v68, v0
	v_mov_b32_e32 v69, v0
	v_mov_b32_e32 v70, v0
	v_mov_b32_e32 v71, v0
	v_mov_b32_e32 v80, v0
	v_mov_b32_e32 v81, v0
	v_mov_b32_e32 v82, v0
	v_mov_b32_e32 v83, v0
	v_mov_b32_e32 v84, v0
	v_mov_b32_e32 v85, v0
	v_mov_b32_e32 v86, v0
	v_mov_b32_e32 v87, v0
	v_mov_b32_e32 v96, v0
	v_mov_b32_e32 v97, v0
	v_mov_b32_e32 v98, v0
	v_mov_b32_e32 v99, v0
	v_mov_b32_e32 v100, v0
	v_mov_b32_e32 v101, v0
	v_mov_b32_e32 v102, v0
	v_mov_b32_e32 v103, v0
	v_mov_b32_e32 v112, v0
	v_mov_b32_e32 v113, v0
	v_mov_b32_e32 v114, v0
	v_mov_b32_e32 v115, v0
	v_mov_b32_e32 v116, v0
	v_mov_b32_e32 v117, v0
	v_mov_b32_e32 v118, v0
	v_mov_b32_e32 v119, v0
	v_mov_b32_e32 v72, v0
	v_mov_b32_e32 v73, v0
	v_mov_b32_e32 v74, v0
	v_mov_b32_e32 v75, v0
	v_mov_b32_e32 v76, v0
	v_mov_b32_e32 v77, v0
	v_mov_b32_e32 v78, v0
	v_mov_b32_e32 v79, v0
	v_mov_b32_e32 v88, v0
	v_mov_b32_e32 v89, v0
	v_mov_b32_e32 v90, v0
	v_mov_b32_e32 v91, v0
	v_mov_b32_e32 v92, v0
	v_mov_b32_e32 v93, v0
	v_mov_b32_e32 v94, v0
	v_mov_b32_e32 v95, v0
	v_mov_b32_e32 v104, v0
	v_mov_b32_e32 v105, v0
	v_mov_b32_e32 v106, v0
	v_mov_b32_e32 v107, v0
	v_mov_b32_e32 v108, v0
	v_mov_b32_e32 v109, v0
	v_mov_b32_e32 v110, v0
	v_mov_b32_e32 v111, v0
	v_mov_b32_e32 v120, v0
	v_mov_b32_e32 v121, v0
	v_mov_b32_e32 v122, v0
	v_mov_b32_e32 v123, v0
	v_mov_b32_e32 v124, v0
	v_mov_b32_e32 v125, v0
	v_mov_b32_e32 v126, v0
	v_mov_b32_e32 v127, v0
	.p2alignl 6, 3212836864

; template <class Epi>
; DEVI void gemm_phase(LAS unsigned char* lds, const bf16_t* gA, const bf16_t* gBt, const int lda, const int ldb, const int K, const StaticOrder S_, const Epi E) {
;     ...
;     for (;;) {
;         const bool has_next = S_.next(ui + 1, nxt);
;         const char* nA = has_next ? (const char*)gA + (size_t)nxt.pm * tstepA : cA; const char* nB = has_next ? (const char*)gBt + (size_t)nxt.pn * tstepB : cB;
;         for (int t = 0; t < nt; t += 2) {
;             const bool last = (t == nt - 2);
;             const char* a1 = cA + (size_t)(t + 1) * kstep;
;             const char* a2 = last ? nA : cA + (size_t)(t + 2) * kstep; const char* b2 = last ? nB : cB + (size_t)(t + 2) * kstep;
;     ...
;         for (int a = 0; a < 2; ++a)
; #pragma unroll
;             for (int b = 0; b < 2; ++b)
; #pragma unroll
;                 for (int m = 0; m < 4; ++m)
; #pragma unroll
;                     for (int n = 0; n < 2; ++n) acc[a][b][m][n] = (f32x4){0.f, 0.f, 0.f, 0.f};
.LBB0_2364:
	v_mov_b32_e32 v127, 0
	s_andn2_b64 vcc, exec, s[10:11]
	v_mov_b32_e32 v126, v127
	v_mov_b32_e32 v125, v127
	v_mov_b32_e32 v124, v127
	v_mov_b32_e32 v123, v127
	v_mov_b32_e32 v122, v127
	v_mov_b32_e32 v121, v127
	v_mov_b32_e32 v120, v127
	v_mov_b32_e32 v111, v127
	v_mov_b32_e32 v110, v127
	v_mov_b32_e32 v109, v127
	v_mov_b32_e32 v108, v127
	v_mov_b32_e32 v107, v127
	v_mov_b32_e32 v106, v127
	v_mov_b32_e32 v105, v127
	v_mov_b32_e32 v104, v127
	v_mov_b32_e32 v95, v127
	v_mov_b32_e32 v94, v127
	v_mov_b32_e32 v93, v127
	v_mov_b32_e32 v92, v127
	v_mov_b32_e32 v91, v127
	v_mov_b32_e32 v90, v127
	v_mov_b32_e32 v89, v127
	v_mov_b32_e32 v88, v127
	v_mov_b32_e32 v79, v127
	v_mov_b32_e32 v78, v127
	v_mov_b32_e32 v77, v127
	v_mov_b32_e32 v76, v127
	v_mov_b32_e32 v75, v127
	v_mov_b32_e32 v74, v127
	v_mov_b32_e32 v73, v127
	v_mov_b32_e32 v72, v127
	v_mov_b32_e32 v119, v127
	v_mov_b32_e32 v118, v127
	v_mov_b32_e32 v117, v127
	v_mov_b32_e32 v116, v127
	v_mov_b32_e32 v115, v127
	v_mov_b32_e32 v114, v127
	v_mov_b32_e32 v113, v127
	v_mov_b32_e32 v112, v127
	v_mov_b32_e32 v103, v127
	v_mov_b32_e32 v102, v127
	v_mov_b32_e32 v101, v127
	v_mov_b32_e32 v100, v127
	v_mov_b32_e32 v99, v127
	v_mov_b32_e32 v98, v127
	v_mov_b32_e32 v97, v127
	v_mov_b32_e32 v96, v127
	v_mov_b32_e32 v87, v127
	v_mov_b32_e32 v86, v127
	v_mov_b32_e32 v85, v127
	v_mov_b32_e32 v84, v127
	v_mov_b32_e32 v83, v127
	v_mov_b32_e32 v82, v127
	v_mov_b32_e32 v81, v127
	v_mov_b32_e32 v80, v127
	v_mov_b32_e32 v71, v127
	v_mov_b32_e32 v70, v127
	v_mov_b32_e32 v69, v127
	v_mov_b32_e32 v68, v127
	v_mov_b32_e32 v67, v127
	v_mov_b32_e32 v66, v127
	v_mov_b32_e32 v65, v127
	v_mov_b32_e32 v64, v127
	v_mov_b32_e32 v63, v127
	v_mov_b32_e32 v62, v127
	v_mov_b32_e32 v61, v127
	v_mov_b32_e32 v60, v127
	v_mov_b32_e32 v59, v127
	v_mov_b32_e32 v58, v127
	v_mov_b32_e32 v57, v127
	v_mov_b32_e32 v56, v127
	v_mov_b32_e32 v47, v127
	v_mov_b32_e32 v46, v127
	v_mov_b32_e32 v45, v127
	v_mov_b32_e32 v44, v127
	v_mov_b32_e32 v43, v127
	v_mov_b32_e32 v42, v127
	v_mov_b32_e32 v41, v127
	v_mov_b32_e32 v40, v127
	v_mov_b32_e32 v31, v127
	v_mov_b32_e32 v30, v127
	v_mov_b32_e32 v29, v127
	v_mov_b32_e32 v28, v127
	v_mov_b32_e32 v27, v127
	v_mov_b32_e32 v26, v127
	v_mov_b32_e32 v25, v127
	v_mov_b32_e32 v24, v127
	v_mov_b32_e32 v15, v127
	v_mov_b32_e32 v14, v127
	v_mov_b32_e32 v13, v127
	v_mov_b32_e32 v12, v127
	v_mov_b32_e32 v11, v127
	v_mov_b32_e32 v10, v127
	v_mov_b32_e32 v9, v127
	v_mov_b32_e32 v8, v127
	v_mov_b32_e32 v55, v127
	v_mov_b32_e32 v54, v127
	v_mov_b32_e32 v53, v127
	v_mov_b32_e32 v52, v127
	v_mov_b32_e32 v51, v127
	v_mov_b32_e32 v50, v127
	v_mov_b32_e32 v49, v127
	v_mov_b32_e32 v48, v127
	v_mov_b32_e32 v39, v127
	v_mov_b32_e32 v38, v127
	v_mov_b32_e32 v37, v127
	v_mov_b32_e32 v36, v127
	v_mov_b32_e32 v35, v127
	v_mov_b32_e32 v34, v127
	v_mov_b32_e32 v33, v127
	v_mov_b32_e32 v32, v127
	v_mov_b32_e32 v23, v127
	v_mov_b32_e32 v22, v127
	v_mov_b32_e32 v21, v127
	v_mov_b32_e32 v20, v127
	v_mov_b32_e32 v19, v127
	v_mov_b32_e32 v18, v127
	v_mov_b32_e32 v17, v127
	v_mov_b32_e32 v16, v127
	v_mov_b32_e32 v7, v127
	v_mov_b32_e32 v6, v127
	v_mov_b32_e32 v5, v127
	v_mov_b32_e32 v4, v127
	v_mov_b32_e32 v3, v127
	v_mov_b32_e32 v2, v127
	s_waitcnt lgkmcnt(0)
	v_mov_b32_e32 v1, v127
	v_mov_b32_e32 v0, v127
	s_cbranch_vccnz .LBB0_2367
	s_add_u32 s14, s14, 0x80
	s_addc_u32 s15, s15, 0
	s_add_u32 s48, s48, 0x100
	v_mov_b32_e32 v0, 0
	s_addc_u32 s49, s49, 0
	s_mov_b32 s16, 0
	v_mov_b32_e32 v1, v0
	v_mov_b32_e32 v2, v0
	v_mov_b32_e32 v3, v0
	v_mov_b32_e32 v4, v0
	v_mov_b32_e32 v5, v0
	v_mov_b32_e32 v6, v0
	v_mov_b32_e32 v7, v0
	v_mov_b32_e32 v16, v0
	v_mov_b32_e32 v17, v0
	v_mov_b32_e32 v18, v0
	v_mov_b32_e32 v19, v0
	v_mov_b32_e32 v20, v0
	v_mov_b32_e32 v21, v0
	v_mov_b32_e32 v22, v0
	v_mov_b32_e32 v23, v0
	v_mov_b32_e32 v32, v0
	v_mov_b32_e32 v33, v0
	v_mov_b32_e32 v34, v0
	v_mov_b32_e32 v35, v0
	v_mov_b32_e32 v36, v0
	v_mov_b32_e32 v37, v0
	v_mov_b32_e32 v38, v0
	v_mov_b32_e32 v39, v0
	v_mov_b32_e32 v48, v0
	v_mov_b32_e32 v49, v0
	v_mov_b32_e32 v50, v0
	v_mov_b32_e32 v51, v0
	v_mov_b32_e32 v52, v0
	v_mov_b32_e32 v53, v0
	v_mov_b32_e32 v54, v0
	v_mov_b32_e32 v55, v0
	v_mov_b32_e32 v8, v0
	v_mov_b32_e32 v9, v0
	v_mov_b32_e32 v10, v0
	v_mov_b32_e32 v11, v0
	v_mov_b32_e32 v12, v0
	v_mov_b32_e32 v13, v0
	v_mov_b32_e32 v14, v0
	v_mov_b32_e32 v15, v0
	v_mov_b32_e32 v24, v0
	v_mov_b32_e32 v25, v0
	v_mov_b32_e32 v26, v0
	v_mov_b32_e32 v27, v0
	v_mov_b32_e32 v28, v0
	v_mov_b32_e32 v29, v0
	v_mov_b32_e32 v30, v0
	v_mov_b32_e32 v31, v0
	v_mov_b32_e32 v40, v0
	v_mov_b32_e32 v41, v0
	v_mov_b32_e32 v42, v0
	v_mov_b32_e32 v43, v0
	v_mov_b32_e32 v44, v0
	v_mov_b32_e32 v45, v0
	v_mov_b32_e32 v46, v0
	v_mov_b32_e32 v47, v0
	v_mov_b32_e32 v56, v0
	v_mov_b32_e32 v57, v0
	v_mov_b32_e32 v58, v0
	v_mov_b32_e32 v59, v0
	v_mov_b32_e32 v60, v0
	v_mov_b32_e32 v61, v0
	v_mov_b32_e32 v62, v0
	v_mov_b32_e32 v63, v0
	v_mov_b32_e32 v64, v0
	v_mov_b32_e32 v65, v0
	v_mov_b32_e32 v66, v0
	v_mov_b32_e32 v67, v0
	v_mov_b32_e32 v68, v0
	v_mov_b32_e32 v69, v0
	v_mov_b32_e32 v70, v0
	v_mov_b32_e32 v71, v0
	v_mov_b32_e32 v80, v0
	v_mov_b32_e32 v81, v0
	v_mov_b32_e32 v82, v0
	v_mov_b32_e32 v83, v0
	v_mov_b32_e32 v84, v0
	v_mov_b32_e32 v85, v0
	v_mov_b32_e32 v86, v0
	v_mov_b32_e32 v87, v0
	v_mov_b32_e32 v96, v0
	v_mov_b32_e32 v97, v0
	v_mov_b32_e32 v98, v0
	v_mov_b32_e32 v99, v0
	v_mov_b32_e32 v100, v0
	v_mov_b32_e32 v101, v0
	v_mov_b32_e32 v102, v0
	v_mov_b32_e32 v103, v0
	v_mov_b32_e32 v112, v0
	v_mov_b32_e32 v113, v0
	v_mov_b32_e32 v114, v0
	v_mov_b32_e32 v115, v0
	v_mov_b32_e32 v116, v0
	v_mov_b32_e32 v117, v0
	v_mov_b32_e32 v118, v0
	v_mov_b32_e32 v119, v0
	v_mov_b32_e32 v72, v0
	v_mov_b32_e32 v73, v0
	v_mov_b32_e32 v74, v0
	v_mov_b32_e32 v75, v0
	v_mov_b32_e32 v76, v0
	v_mov_b32_e32 v77, v0
	v_mov_b32_e32 v78, v0
	v_mov_b32_e32 v79, v0
	v_mov_b32_e32 v88, v0
	v_mov_b32_e32 v89, v0
	v_mov_b32_e32 v90, v0
	v_mov_b32_e32 v91, v0
	v_mov_b32_e32 v92, v0
	v_mov_b32_e32 v93, v0
	v_mov_b32_e32 v94, v0
	v_mov_b32_e32 v95, v0
	v_mov_b32_e32 v104, v0
	v_mov_b32_e32 v105, v0
	v_mov_b32_e32 v106, v0
	v_mov_b32_e32 v107, v0
	v_mov_b32_e32 v108, v0
	v_mov_b32_e32 v109, v0
	v_mov_b32_e32 v110, v0
	v_mov_b32_e32 v111, v0
	v_mov_b32_e32 v120, v0
	v_mov_b32_e32 v121, v0
	v_mov_b32_e32 v122, v0
	v_mov_b32_e32 v123, v0
	v_mov_b32_e32 v124, v0
	v_mov_b32_e32 v125, v0
	v_mov_b32_e32 v126, v0
	v_mov_b32_e32 v127, v0
	s_waitcnt vmcnt(0)
	.p2alignl 6, 3212836864

; template <class Epi>
; DEVI void gemm_phase(LAS unsigned char* lds, const bf16_t* gA, const bf16_t* gBt, const int lda, const int ldb, const int K, const StaticOrder S_, const Epi E) {
;     ...
;     for (;;) {
;         const bool has_next = S_.next(ui + 1, nxt);
;         const char* nA = has_next ? (const char*)gA + (size_t)nxt.pm * tstepA : cA; const char* nB = has_next ? (const char*)gBt + (size_t)nxt.pn * tstepB : cB;
;         for (int t = 0; t < nt; t += 2) {
;             const bool last = (t == nt - 2);
;             const char* a1 = cA + (size_t)(t + 1) * kstep;
;             const char* a2 = last ? nA : cA + (size_t)(t + 2) * kstep; const char* b2 = last ? nB : cB + (size_t)(t + 2) * kstep;
;     ...
;         for (int a = 0; a < 2; ++a)
; #pragma unroll
;             for (int b = 0; b < 2; ++b)
; #pragma unroll
;                 for (int m = 0; m < 4; ++m)
; #pragma unroll
;                     for (int n = 0; n < 2; ++n) acc[a][b][m][n] = (f32x4){0.f, 0.f, 0.f, 0.f};
.LBB0_2508:
	v_mov_b32_e32 v123, 0
	s_andn2_b64 vcc, exec, s[42:43]
	v_mov_b32_e32 v122, v123
	v_mov_b32_e32 v121, v123
	v_mov_b32_e32 v120, v123
	v_mov_b32_e32 v119, v123
	v_mov_b32_e32 v118, v123
	v_mov_b32_e32 v117, v123
	v_mov_b32_e32 v116, v123
	v_mov_b32_e32 v111, v123
	v_mov_b32_e32 v110, v123
	v_mov_b32_e32 v109, v123
	v_mov_b32_e32 v108, v123
	v_mov_b32_e32 v103, v123
	v_mov_b32_e32 v102, v123
	v_mov_b32_e32 v101, v123
	v_mov_b32_e32 v100, v123
	v_mov_b32_e32 v95, v123
	v_mov_b32_e32 v94, v123
	v_mov_b32_e32 v93, v123
	v_mov_b32_e32 v92, v123
	v_mov_b32_e32 v87, v123
	v_mov_b32_e32 v86, v123
	v_mov_b32_e32 v85, v123
	v_mov_b32_e32 v84, v123
	v_mov_b32_e32 v79, v123
	v_mov_b32_e32 v78, v123
	v_mov_b32_e32 v77, v123
	v_mov_b32_e32 v76, v123
	v_mov_b32_e32 v71, v123
	v_mov_b32_e32 v70, v123
	v_mov_b32_e32 v69, v123
	v_mov_b32_e32 v68, v123
	v_mov_b32_e32 v127, v123
	v_mov_b32_e32 v126, v123
	v_mov_b32_e32 v125, v123
	v_mov_b32_e32 v124, v123
	v_mov_b32_e32 v115, v123
	v_mov_b32_e32 v114, v123
	v_mov_b32_e32 v113, v123
	v_mov_b32_e32 v112, v123
	v_mov_b32_e32 v107, v123
	v_mov_b32_e32 v106, v123
	v_mov_b32_e32 v105, v123
	v_mov_b32_e32 v104, v123
	v_mov_b32_e32 v99, v123
	v_mov_b32_e32 v98, v123
	v_mov_b32_e32 v97, v123
	v_mov_b32_e32 v96, v123
	v_mov_b32_e32 v91, v123
	v_mov_b32_e32 v90, v123
	v_mov_b32_e32 v89, v123
	v_mov_b32_e32 v88, v123
	v_mov_b32_e32 v83, v123
	v_mov_b32_e32 v82, v123
	v_mov_b32_e32 v81, v123
	v_mov_b32_e32 v80, v123
	v_mov_b32_e32 v75, v123
	v_mov_b32_e32 v74, v123
	v_mov_b32_e32 v73, v123
	v_mov_b32_e32 v72, v123
	v_mov_b32_e32 v67, v123
	v_mov_b32_e32 v66, v123
	v_mov_b32_e32 v65, v123
	v_mov_b32_e32 v64, v123
	v_mov_b32_e32 v63, v123
	v_mov_b32_e32 v62, v123
	v_mov_b32_e32 v61, v123
	v_mov_b32_e32 v60, v123
	v_mov_b32_e32 v59, v123
	v_mov_b32_e32 v58, v123
	v_mov_b32_e32 v57, v123
	v_mov_b32_e32 v56, v123
	v_mov_b32_e32 v47, v123
	v_mov_b32_e32 v46, v123
	v_mov_b32_e32 v45, v123
	v_mov_b32_e32 v44, v123
	v_mov_b32_e32 v43, v123
	v_mov_b32_e32 v42, v123
	v_mov_b32_e32 v41, v123
	v_mov_b32_e32 v40, v123
	v_mov_b32_e32 v31, v123
	v_mov_b32_e32 v30, v123
	v_mov_b32_e32 v29, v123
	v_mov_b32_e32 v28, v123
	v_mov_b32_e32 v27, v123
	v_mov_b32_e32 v26, v123
	v_mov_b32_e32 v25, v123
	v_mov_b32_e32 v24, v123
	v_mov_b32_e32 v15, v123
	v_mov_b32_e32 v14, v123
	v_mov_b32_e32 v13, v123
	v_mov_b32_e32 v12, v123
	v_mov_b32_e32 v11, v123
	v_mov_b32_e32 v10, v123
	v_mov_b32_e32 v9, v123
	v_mov_b32_e32 v8, v123
	v_mov_b32_e32 v55, v123
	v_mov_b32_e32 v54, v123
	v_mov_b32_e32 v53, v123
	v_mov_b32_e32 v52, v123
	v_mov_b32_e32 v51, v123
	v_mov_b32_e32 v50, v123
	v_mov_b32_e32 v49, v123
	v_mov_b32_e32 v48, v123
	v_mov_b32_e32 v39, v123
	v_mov_b32_e32 v38, v123
	v_mov_b32_e32 v37, v123
	v_mov_b32_e32 v36, v123
	v_mov_b32_e32 v35, v123
	v_mov_b32_e32 v34, v123
	v_mov_b32_e32 v33, v123
	v_mov_b32_e32 v32, v123
	v_mov_b32_e32 v23, v123
	v_mov_b32_e32 v22, v123
	v_mov_b32_e32 v21, v123
	v_mov_b32_e32 v20, v123
	v_mov_b32_e32 v19, v123
	v_mov_b32_e32 v18, v123
	v_mov_b32_e32 v17, v123
	v_mov_b32_e32 v16, v123
	v_mov_b32_e32 v7, v123
	v_mov_b32_e32 v6, v123
	v_mov_b32_e32 v5, v123
	v_mov_b32_e32 v4, v123
	v_mov_b32_e32 v3, v123
	v_mov_b32_e32 v2, v123
	v_mov_b32_e32 v1, v123
	v_mov_b32_e32 v0, v123
	s_cbranch_vccnz .LBB0_2511
	s_add_u32 s14, s14, 0x80
	s_addc_u32 s15, s15, 0
	s_add_u32 s59, s48, 0x100
	v_mov_b32_e32 v0, 0
	s_addc_u32 s60, s49, 0
	s_mov_b32 s16, 0
	v_mov_b32_e32 v1, v0
	v_mov_b32_e32 v2, v0
	v_mov_b32_e32 v3, v0
	v_mov_b32_e32 v4, v0
	v_mov_b32_e32 v5, v0
	v_mov_b32_e32 v6, v0
	v_mov_b32_e32 v7, v0
	v_mov_b32_e32 v16, v0
	v_mov_b32_e32 v17, v0
	v_mov_b32_e32 v18, v0
	v_mov_b32_e32 v19, v0
	v_mov_b32_e32 v20, v0
	v_mov_b32_e32 v21, v0
	v_mov_b32_e32 v22, v0
	v_mov_b32_e32 v23, v0
	v_mov_b32_e32 v32, v0
	v_mov_b32_e32 v33, v0
	v_mov_b32_e32 v34, v0
	v_mov_b32_e32 v35, v0
	v_mov_b32_e32 v36, v0
	v_mov_b32_e32 v37, v0
	v_mov_b32_e32 v38, v0
	v_mov_b32_e32 v39, v0
	v_mov_b32_e32 v48, v0
	v_mov_b32_e32 v49, v0
	v_mov_b32_e32 v50, v0
	v_mov_b32_e32 v51, v0
	v_mov_b32_e32 v52, v0
	v_mov_b32_e32 v53, v0
	v_mov_b32_e32 v54, v0
	v_mov_b32_e32 v55, v0
	v_mov_b32_e32 v8, v0
	v_mov_b32_e32 v9, v0
	v_mov_b32_e32 v10, v0
	v_mov_b32_e32 v11, v0
	v_mov_b32_e32 v12, v0
	v_mov_b32_e32 v13, v0
	v_mov_b32_e32 v14, v0
	v_mov_b32_e32 v15, v0
	v_mov_b32_e32 v24, v0
	v_mov_b32_e32 v25, v0
	v_mov_b32_e32 v26, v0
	v_mov_b32_e32 v27, v0
	v_mov_b32_e32 v28, v0
	v_mov_b32_e32 v29, v0
	v_mov_b32_e32 v30, v0
	v_mov_b32_e32 v31, v0
	v_mov_b32_e32 v40, v0
	v_mov_b32_e32 v41, v0
	v_mov_b32_e32 v42, v0
	v_mov_b32_e32 v43, v0
	v_mov_b32_e32 v44, v0
	v_mov_b32_e32 v45, v0
	v_mov_b32_e32 v46, v0
	v_mov_b32_e32 v47, v0
	v_mov_b32_e32 v56, v0
	v_mov_b32_e32 v57, v0
	v_mov_b32_e32 v58, v0
	v_mov_b32_e32 v59, v0
	v_mov_b32_e32 v60, v0
	v_mov_b32_e32 v61, v0
	v_mov_b32_e32 v62, v0
	v_mov_b32_e32 v63, v0
	v_mov_b32_e32 v64, v0
	v_mov_b32_e32 v65, v0
	v_mov_b32_e32 v66, v0
	v_mov_b32_e32 v67, v0
	v_mov_b32_e32 v72, v0
	v_mov_b32_e32 v73, v0
	v_mov_b32_e32 v74, v0
	v_mov_b32_e32 v75, v0
	v_mov_b32_e32 v80, v0
	v_mov_b32_e32 v81, v0
	v_mov_b32_e32 v82, v0
	v_mov_b32_e32 v83, v0
	v_mov_b32_e32 v88, v0
	v_mov_b32_e32 v89, v0
	v_mov_b32_e32 v90, v0
	v_mov_b32_e32 v91, v0
	v_mov_b32_e32 v96, v0
	v_mov_b32_e32 v97, v0
	v_mov_b32_e32 v98, v0
	v_mov_b32_e32 v99, v0
	v_mov_b32_e32 v104, v0
	v_mov_b32_e32 v105, v0
	v_mov_b32_e32 v106, v0
	v_mov_b32_e32 v107, v0
	v_mov_b32_e32 v112, v0
	v_mov_b32_e32 v113, v0
	v_mov_b32_e32 v114, v0
	v_mov_b32_e32 v115, v0
	v_mov_b32_e32 v124, v0
	v_mov_b32_e32 v125, v0
	v_mov_b32_e32 v126, v0
	v_mov_b32_e32 v127, v0
	v_mov_b32_e32 v68, v0
	v_mov_b32_e32 v69, v0
	v_mov_b32_e32 v70, v0
	v_mov_b32_e32 v71, v0
	v_mov_b32_e32 v76, v0
	v_mov_b32_e32 v77, v0
	v_mov_b32_e32 v78, v0
	v_mov_b32_e32 v79, v0
	v_mov_b32_e32 v84, v0
	v_mov_b32_e32 v85, v0
	v_mov_b32_e32 v86, v0
	v_mov_b32_e32 v87, v0
	v_mov_b32_e32 v92, v0
	v_mov_b32_e32 v93, v0
	v_mov_b32_e32 v94, v0
	v_mov_b32_e32 v95, v0
	v_mov_b32_e32 v100, v0
	v_mov_b32_e32 v101, v0
	v_mov_b32_e32 v102, v0
	v_mov_b32_e32 v103, v0
	v_mov_b32_e32 v108, v0
	v_mov_b32_e32 v109, v0
	v_mov_b32_e32 v110, v0
	v_mov_b32_e32 v111, v0
	v_mov_b32_e32 v116, v0
	v_mov_b32_e32 v117, v0
	v_mov_b32_e32 v118, v0
	v_mov_b32_e32 v119, v0
	v_mov_b32_e32 v120, v0
	v_mov_b32_e32 v121, v0
	v_mov_b32_e32 v122, v0
	v_mov_b32_e32 v123, v0
	.p2alignl 6, 3212836864

; template <class Epi>
; DEVI void gemm_phase(LAS unsigned char* lds, const bf16_t* gA, const bf16_t* gBt, const int lda, const int ldb, const int K, const StaticOrder S_, const Epi E) {
;     ...
;     for (;;) {
;         const bool has_next = S_.next(ui + 1, nxt);
;         const char* nA = has_next ? (const char*)gA + (size_t)nxt.pm * tstepA : cA; const char* nB = has_next ? (const char*)gBt + (size_t)nxt.pn * tstepB : cB;
;         for (int t = 0; t < nt; t += 2) {
;             const bool last = (t == nt - 2);
;             const char* a1 = cA + (size_t)(t + 1) * kstep;
;             const char* a2 = last ? nA : cA + (size_t)(t + 2) * kstep; const char* b2 = last ? nB : cB + (size_t)(t + 2) * kstep;
;     ...
;         for (int a = 0; a < 2; ++a)
; #pragma unroll
;             for (int b = 0; b < 2; ++b)
; #pragma unroll
;                 for (int m = 0; m < 4; ++m)
; #pragma unroll
;                     for (int n = 0; n < 2; ++n) acc[a][b][m][n] = (f32x4){0.f, 0.f, 0.f, 0.f};
.LBB0_2587:
	v_mov_b32_e32 v127, 0
	s_andn2_b64 vcc, exec, s[18:19]
	v_mov_b32_e32 v126, v127
	v_mov_b32_e32 v125, v127
	v_mov_b32_e32 v124, v127
	v_mov_b32_e32 v123, v127
	v_mov_b32_e32 v122, v127
	v_mov_b32_e32 v121, v127
	v_mov_b32_e32 v120, v127
	v_mov_b32_e32 v111, v127
	v_mov_b32_e32 v110, v127
	v_mov_b32_e32 v109, v127
	v_mov_b32_e32 v108, v127
	v_mov_b32_e32 v107, v127
	v_mov_b32_e32 v106, v127
	v_mov_b32_e32 v105, v127
	v_mov_b32_e32 v104, v127
	v_mov_b32_e32 v95, v127
	v_mov_b32_e32 v94, v127
	v_mov_b32_e32 v93, v127
	v_mov_b32_e32 v92, v127
	v_mov_b32_e32 v91, v127
	v_mov_b32_e32 v90, v127
	v_mov_b32_e32 v89, v127
	v_mov_b32_e32 v88, v127
	v_mov_b32_e32 v79, v127
	v_mov_b32_e32 v78, v127
	v_mov_b32_e32 v77, v127
	v_mov_b32_e32 v76, v127
	v_mov_b32_e32 v75, v127
	v_mov_b32_e32 v74, v127
	v_mov_b32_e32 v73, v127
	v_mov_b32_e32 v72, v127
	v_mov_b32_e32 v119, v127
	v_mov_b32_e32 v118, v127
	v_mov_b32_e32 v117, v127
	v_mov_b32_e32 v116, v127
	v_mov_b32_e32 v115, v127
	v_mov_b32_e32 v114, v127
	v_mov_b32_e32 v113, v127
	v_mov_b32_e32 v112, v127
	v_mov_b32_e32 v103, v127
	v_mov_b32_e32 v102, v127
	v_mov_b32_e32 v101, v127
	v_mov_b32_e32 v100, v127
	v_mov_b32_e32 v99, v127
	v_mov_b32_e32 v98, v127
	v_mov_b32_e32 v97, v127
	v_mov_b32_e32 v96, v127
	v_mov_b32_e32 v87, v127
	v_mov_b32_e32 v86, v127
	v_mov_b32_e32 v85, v127
	v_mov_b32_e32 v84, v127
	v_mov_b32_e32 v83, v127
	v_mov_b32_e32 v82, v127
	v_mov_b32_e32 v81, v127
	v_mov_b32_e32 v80, v127
	v_mov_b32_e32 v71, v127
	v_mov_b32_e32 v70, v127
	v_mov_b32_e32 v69, v127
	v_mov_b32_e32 v68, v127
	v_mov_b32_e32 v67, v127
	v_mov_b32_e32 v66, v127
	v_mov_b32_e32 v65, v127
	v_mov_b32_e32 v64, v127
	v_mov_b32_e32 v63, v127
	v_mov_b32_e32 v62, v127
	v_mov_b32_e32 v61, v127
	v_mov_b32_e32 v60, v127
	v_mov_b32_e32 v59, v127
	v_mov_b32_e32 v58, v127
	v_mov_b32_e32 v57, v127
	v_mov_b32_e32 v56, v127
	v_mov_b32_e32 v47, v127
	v_mov_b32_e32 v46, v127
	v_mov_b32_e32 v45, v127
	v_mov_b32_e32 v44, v127
	v_mov_b32_e32 v43, v127
	v_mov_b32_e32 v42, v127
	v_mov_b32_e32 v41, v127
	v_mov_b32_e32 v40, v127
	v_mov_b32_e32 v31, v127
	v_mov_b32_e32 v30, v127
	v_mov_b32_e32 v29, v127
	v_mov_b32_e32 v28, v127
	v_mov_b32_e32 v27, v127
	v_mov_b32_e32 v26, v127
	v_mov_b32_e32 v25, v127
	v_mov_b32_e32 v24, v127
	v_mov_b32_e32 v15, v127
	v_mov_b32_e32 v14, v127
	v_mov_b32_e32 v13, v127
	v_mov_b32_e32 v12, v127
	v_mov_b32_e32 v11, v127
	v_mov_b32_e32 v10, v127
	v_mov_b32_e32 v9, v127
	v_mov_b32_e32 v8, v127
	v_mov_b32_e32 v55, v127
	v_mov_b32_e32 v54, v127
	v_mov_b32_e32 v53, v127
	v_mov_b32_e32 v52, v127
	v_mov_b32_e32 v51, v127
	v_mov_b32_e32 v50, v127
	v_mov_b32_e32 v49, v127
	v_mov_b32_e32 v48, v127
	v_mov_b32_e32 v39, v127
	v_mov_b32_e32 v38, v127
	v_mov_b32_e32 v37, v127
	v_mov_b32_e32 v36, v127
	v_mov_b32_e32 v35, v127
	v_mov_b32_e32 v34, v127
	v_mov_b32_e32 v33, v127
	v_mov_b32_e32 v32, v127
	v_mov_b32_e32 v23, v127
	v_mov_b32_e32 v22, v127
	v_mov_b32_e32 v21, v127
	v_mov_b32_e32 v20, v127
	v_mov_b32_e32 v19, v127
	v_mov_b32_e32 v18, v127
	v_mov_b32_e32 v17, v127
	v_mov_b32_e32 v16, v127
	v_mov_b32_e32 v7, v127
	v_mov_b32_e32 v6, v127
	v_mov_b32_e32 v5, v127
	v_mov_b32_e32 v4, v127
	v_mov_b32_e32 v3, v127
	v_mov_b32_e32 v2, v127
	s_waitcnt lgkmcnt(0)
	v_mov_b32_e32 v1, v127
	v_mov_b32_e32 v0, v127
	s_cbranch_vccnz .LBB0_2591
	s_add_u32 s4, s26, 0x80
	s_addc_u32 s5, s27, 0
	s_add_u32 s54, s24, 0x100
	v_mov_b32_e32 v0, 0
	s_addc_u32 s55, s25, 0
	s_mov_b32 s24, 0
	v_mov_b32_e32 v1, v0
	v_mov_b32_e32 v2, v0
	v_mov_b32_e32 v3, v0
	v_mov_b32_e32 v4, v0
	v_mov_b32_e32 v5, v0
	v_mov_b32_e32 v6, v0
	v_mov_b32_e32 v7, v0
	v_mov_b32_e32 v16, v0
	v_mov_b32_e32 v17, v0
	v_mov_b32_e32 v18, v0
	v_mov_b32_e32 v19, v0
	v_mov_b32_e32 v20, v0
	v_mov_b32_e32 v21, v0
	v_mov_b32_e32 v22, v0
	v_mov_b32_e32 v23, v0
	v_mov_b32_e32 v32, v0
	v_mov_b32_e32 v33, v0
	v_mov_b32_e32 v34, v0
	v_mov_b32_e32 v35, v0
	v_mov_b32_e32 v36, v0
	v_mov_b32_e32 v37, v0
	v_mov_b32_e32 v38, v0
	v_mov_b32_e32 v39, v0
	v_mov_b32_e32 v48, v0
	v_mov_b32_e32 v49, v0
	v_mov_b32_e32 v50, v0
	v_mov_b32_e32 v51, v0
	v_mov_b32_e32 v52, v0
	v_mov_b32_e32 v53, v0
	v_mov_b32_e32 v54, v0
	v_mov_b32_e32 v55, v0
	v_mov_b32_e32 v8, v0
	v_mov_b32_e32 v9, v0
	v_mov_b32_e32 v10, v0
	v_mov_b32_e32 v11, v0
	v_mov_b32_e32 v12, v0
	v_mov_b32_e32 v13, v0
	v_mov_b32_e32 v14, v0
	v_mov_b32_e32 v15, v0
	v_mov_b32_e32 v24, v0
	v_mov_b32_e32 v25, v0
	v_mov_b32_e32 v26, v0
	v_mov_b32_e32 v27, v0
	v_mov_b32_e32 v28, v0
	v_mov_b32_e32 v29, v0
	v_mov_b32_e32 v30, v0
	v_mov_b32_e32 v31, v0
	v_mov_b32_e32 v40, v0
	v_mov_b32_e32 v41, v0
	v_mov_b32_e32 v42, v0
	v_mov_b32_e32 v43, v0
	v_mov_b32_e32 v44, v0
	v_mov_b32_e32 v45, v0
	v_mov_b32_e32 v46, v0
	v_mov_b32_e32 v47, v0
	v_mov_b32_e32 v56, v0
	v_mov_b32_e32 v57, v0
	v_mov_b32_e32 v58, v0
	v_mov_b32_e32 v59, v0
	v_mov_b32_e32 v60, v0
	v_mov_b32_e32 v61, v0
	v_mov_b32_e32 v62, v0
	v_mov_b32_e32 v63, v0
	v_mov_b32_e32 v64, v0
	v_mov_b32_e32 v65, v0
	v_mov_b32_e32 v66, v0
	v_mov_b32_e32 v67, v0
	v_mov_b32_e32 v68, v0
	v_mov_b32_e32 v69, v0
	v_mov_b32_e32 v70, v0
	v_mov_b32_e32 v71, v0
	v_mov_b32_e32 v80, v0
	v_mov_b32_e32 v81, v0
	v_mov_b32_e32 v82, v0
	v_mov_b32_e32 v83, v0
	v_mov_b32_e32 v84, v0
	v_mov_b32_e32 v85, v0
	v_mov_b32_e32 v86, v0
	v_mov_b32_e32 v87, v0
	v_mov_b32_e32 v96, v0
	v_mov_b32_e32 v97, v0
	v_mov_b32_e32 v98, v0
	v_mov_b32_e32 v99, v0
	v_mov_b32_e32 v100, v0
	v_mov_b32_e32 v101, v0
	v_mov_b32_e32 v102, v0
	v_mov_b32_e32 v103, v0
	v_mov_b32_e32 v112, v0
	v_mov_b32_e32 v113, v0
	v_mov_b32_e32 v114, v0
	v_mov_b32_e32 v115, v0
	v_mov_b32_e32 v116, v0
	v_mov_b32_e32 v117, v0
	v_mov_b32_e32 v118, v0
	v_mov_b32_e32 v119, v0
	v_mov_b32_e32 v72, v0
	v_mov_b32_e32 v73, v0
	v_mov_b32_e32 v74, v0
	v_mov_b32_e32 v75, v0
	v_mov_b32_e32 v76, v0
	v_mov_b32_e32 v77, v0
	v_mov_b32_e32 v78, v0
	v_mov_b32_e32 v79, v0
	v_mov_b32_e32 v88, v0
	v_mov_b32_e32 v89, v0
	v_mov_b32_e32 v90, v0
	v_mov_b32_e32 v91, v0
	v_mov_b32_e32 v92, v0
	v_mov_b32_e32 v93, v0
	v_mov_b32_e32 v94, v0
	v_mov_b32_e32 v95, v0
	v_mov_b32_e32 v104, v0
	v_mov_b32_e32 v105, v0
	v_mov_b32_e32 v106, v0
	v_mov_b32_e32 v107, v0
	v_mov_b32_e32 v108, v0
	v_mov_b32_e32 v109, v0
	v_mov_b32_e32 v110, v0
	v_mov_b32_e32 v111, v0
	v_mov_b32_e32 v120, v0
	v_mov_b32_e32 v121, v0
	v_mov_b32_e32 v122, v0
	v_mov_b32_e32 v123, v0
	v_mov_b32_e32 v124, v0
	v_mov_b32_e32 v125, v0
	v_mov_b32_e32 v126, v0
	v_mov_b32_e32 v127, v0
	.p2alignl 6, 3212836864
